# attention loop lean: pairwise P.V waits, h=2 tile DMA unconditional (no in-stream branches), fewer s_nop
# speedup vs baseline: 1.0466x; 1.0027x over previous
; #define SBAR() __builtin_amdgcn_sched_barrier(0)
; __device__ __forceinline__ void partialSM_fix(f32x16& p0) { for (int r = 0; r < 16; ++r) p0[r] = __builtin_amdgcn_exp2f(p0[r]); }
; #define SLOAD(i, k0) do { sr_[i].vs0 = St::ld8(&Vh[(long)((k0) + sr) * LDK + sc]); sr_[i].vs1 = St::ld8(&Vh[(long)((k0) + 32 + sr) * LDK + sc]); \
;     sr_[i].ks0 = St::ld8(&Kh[(long)((k0) + sr) * LDK + sc]); sr_[i].ks1 = St::ld8(&Kh[(long)((k0) + 32 + sr) * LDK + sc]); } while (0)
; #define SWAIT() do { if constexpr (SDEPTH == 2) asm volatile("s_waitcnt vmcnt(4)" ::: "memory"); else asm volatile("s_waitcnt vmcnt(0)" ::: "memory"); } while (0)
; template <int D0> __device__ __forceinline__ void pv_one(f32x16& od, int vb, bf16x8 pa0, bf16x8 pa1, bf16x8 pa2, bf16x8 pa3) {
;   const s16x4 l0 = tr_read<v_rd_off(D0, 0, 0)>(vb), h0 = tr_read<v_rd_off(D0, 0, 1)>(vb), l1 = tr_read<v_rd_off(D0, 1, 0)>(vb), h1 = tr_read<v_rd_off(D0, 1, 1)>(vb);
;   const s16x4 l2 = tr_read<v_rd_off(D0, 2, 0)>(vb), h2 = tr_read<v_rd_off(D0, 2, 1)>(vb), l3 = tr_read<v_rd_off(D0, 3, 0)>(vb), h3 = tr_read<v_rd_off(D0, 3, 1)>(vb);
;   asm volatile("s_waitcnt lgkmcnt(0)" ::: "memory"); SBAR();
;     ...
;   od = __builtin_amdgcn_mfma_f32_32x32x16_bf16(pa0, PK(l0, h0), od, 0, 0, 0);
;   od = __builtin_amdgcn_mfma_f32_32x32x16_bf16(pa1, PK(l1, h1), od, 0, 0, 0);
;   od = __builtin_amdgcn_mfma_f32_32x32x16_bf16(pa2, PK(l2, h2), od, 0, 0, 0);
;   od = __builtin_amdgcn_mfma_f32_32x32x16_bf16(pa3, PK(l3, h3), od, 0, 0, 0);
;     ...
; }
; __device__ __forceinline__ void pv_d0(f32x16* o, int vb, bf16x8 pa0, bf16x8 pa1, bf16x8 pa2, bf16x8 pa3) {
;   pv_one<0>(o[0], vb, pa0, pa1, pa2, pa3); pv_one<1>(o[1], vb, pa0, pa1, pa2, pa3); pv_one<2>(o[2], vb, pa0, pa1, pa2, pa3); pv_one<3>(o[3], vb, pa0, pa1, pa2, pa3);
; }
; template <typename TQ>
; __device__ __forceinline__ void attn_dense_body(const TQ* __restrict__ Qb, const bf16* __restrict__ Kh, const bf16* __restrict__ Vh,
;                                                 bf16* __restrict__ Ob, int seq, char* lds) {
;     ...
;     SBAR(); qkt(pB0, pB1, (bf16*)((char*)K_lds + cur * (int)SHM_K), qr, r32, hi);
;     finishSM(pA0, pA1, alA, l_reg, pa0, pa1, pa2, pa3); SBAR();
;     SWAIT(); SWRITE(next, SE);
;     if (j + 2 < NT) SLOAD(SO, (j + 2) * KVBLK); SBAR();
;     pv_d0(o, vb0 + prev * (int)SHM_V, pa0, pa1, pa2, pa3); partialSM_fix(pB0);
;     __syncthreads();
.Latt_loop:
	s_waitcnt lgkmcnt(4)
	v_mfma_f32_32x32x16_bf16 v[96:111], v[208:211], v[140:143], 0
	v_exp_f32_e32 v64, v64
	v_exp_f32_e32 v65, v65
	v_cvt_pk_bf16_f32 v224, v224, v225
	v_mfma_f32_32x32x16_bf16 v[80:95], v[212:215], v[140:143], 0
	ds_read_b128 v[208:211], v147 offset:16384
	ds_read_b128 v[212:215], v147 offset:24576
	v_exp_f32_e32 v66, v66
	v_exp_f32_e32 v67, v67
	v_cvt_pk_bf16_f32 v225, v226, v227
	s_waitcnt lgkmcnt(4)
	v_mfma_f32_32x32x16_bf16 v[96:111], v[216:219], v[136:139], v[96:111]
	v_exp_f32_e32 v68, v68
	v_exp_f32_e32 v69, v69
	v_cvt_pk_bf16_f32 v226, v228, v229
	v_mfma_f32_32x32x16_bf16 v[80:95], v[220:223], v[136:139], v[80:95]
	ds_read_b128 v[216:219], v148 offset:16384
	ds_read_b128 v[220:223], v148 offset:24576
	v_exp_f32_e32 v70, v70
	v_exp_f32_e32 v71, v71
	v_cvt_pk_bf16_f32 v227, v230, v231
	v_add_f32_e32 v251, v64, v66
	s_waitcnt lgkmcnt(4)
	v_mfma_f32_32x32x16_bf16 v[96:111], v[240:243], v[132:135], v[96:111]
	v_exp_f32_e32 v72, v72
	v_exp_f32_e32 v73, v73
	v_add_f32_e32 v253, v65, v67
	v_mfma_f32_32x32x16_bf16 v[80:95], v[244:247], v[132:135], v[80:95]
	ds_read_b128 v[240:243], v149 offset:16384
	ds_read_b128 v[244:247], v149 offset:24576
	v_exp_f32_e32 v74, v74
	v_exp_f32_e32 v75, v75
	v_add_f32_e32 v251, v251, v68
	s_waitcnt lgkmcnt(4)
	v_mfma_f32_32x32x16_bf16 v[96:111], v[208:211], v[128:131], v[96:111]
	v_exp_f32_e32 v76, v76
	v_exp_f32_e32 v77, v77
	v_add_f32_e32 v253, v253, v69
	v_cvt_pk_bf16_f32 v228, v232, v233
	v_mfma_f32_32x32x16_bf16 v[80:95], v[212:215], v[128:131], v[80:95]
	ds_read_b128 v[208:211], v150 offset:16384
	ds_read_b128 v[212:215], v150 offset:24576
	v_exp_f32_e32 v78, v78
	v_exp_f32_e32 v79, v79
	v_add_f32_e32 v251, v251, v70
	v_cvt_pk_bf16_f32 v229, v234, v235
	s_waitcnt lgkmcnt(4)
	v_mfma_f32_32x32x16_bf16 v[96:111], v[216:219], v[124:127], v[96:111]
	v_add_f32_e32 v253, v253, v71
	v_cvt_pk_bf16_f32 v230, v236, v237
	v_cvt_pk_bf16_f32 v231, v238, v239
	v_add_f32_e32 v251, v251, v72
	v_mfma_f32_32x32x16_bf16 v[80:95], v[220:223], v[124:127], v[80:95]
	ds_read_b128 v[216:219], v151 offset:16384
	ds_read_b128 v[220:223], v151 offset:24576
	v_add_f32_e32 v253, v253, v73
	v_cvt_pk_bf16_f32 v232, v64, v65
	v_cvt_pk_bf16_f32 v233, v66, v67
	s_waitcnt lgkmcnt(4)
	v_mfma_f32_32x32x16_bf16 v[96:111], v[240:243], v[120:123], v[96:111]
	v_add_f32_e32 v251, v251, v74
	v_cvt_pk_bf16_f32 v234, v68, v69
	v_cvt_pk_bf16_f32 v235, v70, v71
	v_mfma_f32_32x32x16_bf16 v[80:95], v[244:247], v[120:123], v[80:95]
	ds_read_b64_tr_b16 v[240:241], v179 offset:0
	ds_read_b64_tr_b16 v[242:243], v179 offset:2048
	ds_read_b64_tr_b16 v[244:245], v179 offset:4096
	ds_read_b64_tr_b16 v[246:247], v179 offset:6144
	v_add_f32_e32 v253, v253, v75
	v_add_f32_e32 v251, v251, v76
	v_cvt_pk_bf16_f32 v236, v72, v73
	v_cvt_pk_bf16_f32 v237, v74, v75
	s_waitcnt lgkmcnt(6)
	v_mfma_f32_32x32x16_bf16 v[96:111], v[208:211], v[116:119], v[96:111]
	v_add_f32_e32 v253, v253, v77
	v_add_f32_e32 v251, v251, v78
	v_mfma_f32_32x32x16_bf16 v[80:95], v[212:215], v[116:119], v[80:95]
	ds_read_b64_tr_b16 v[208:209], v179 offset:8192
	ds_read_b64_tr_b16 v[210:211], v179 offset:10240
	ds_read_b64_tr_b16 v[212:213], v179 offset:12288
	ds_read_b64_tr_b16 v[214:215], v179 offset:14336
	v_add_f32_e32 v253, v253, v79
	v_cvt_pk_bf16_f32 v238, v76, v77
	v_cvt_pk_bf16_f32 v239, v78, v79
	s_waitcnt lgkmcnt(8)
	v_mfma_f32_32x32x16_bf16 v[96:111], v[216:219], v[112:115], v[96:111]
	v_add_f32_e32 v251, v251, v253
	v_add_f32_e32 v254, v254, v251
	v_mfma_f32_32x32x16_bf16 v[80:95], v[220:223], v[112:115], v[80:95]
	ds_read_b64_tr_b16 v[216:217], v179 offset:512
	ds_read_b64_tr_b16 v[218:219], v179 offset:2560
	ds_read_b64_tr_b16 v[220:221], v179 offset:4608
	ds_read_b64_tr_b16 v[222:223], v179 offset:6656
	v_add_f32_e32 v169, v169, v254
	s_waitcnt lgkmcnt(8)
	v_mfma_f32_32x32x16_bf16 v[0:15], v[224:227], v[240:243], v[0:15]
	ds_read_b64_tr_b16 v[64:65], v179 offset:8704
	ds_read_b64_tr_b16 v[66:67], v179 offset:10752
	v_mfma_f32_32x32x16_bf16 v[0:15], v[228:231], v[244:247], v[0:15]
	ds_read_b64_tr_b16 v[68:69], v179 offset:12800
	ds_read_b64_tr_b16 v[70:71], v179 offset:14848
	v_exp_f32_e32 v96, v96
	v_exp_f32_e32 v97, v97
	s_waitcnt lgkmcnt(8)
	v_mfma_f32_32x32x16_bf16 v[0:15], v[232:235], v[208:211], v[0:15]
	ds_read_b64_tr_b16 v[72:73], v179 offset:1024
	ds_read_b64_tr_b16 v[74:75], v179 offset:3072
	v_exp_f32_e32 v98, v98
	v_exp_f32_e32 v99, v99
	v_mfma_f32_32x32x16_bf16 v[0:15], v[236:239], v[212:215], v[0:15]
	ds_read_b64_tr_b16 v[76:77], v179 offset:5120
	ds_read_b64_tr_b16 v[78:79], v179 offset:7168
	v_exp_f32_e32 v100, v100
	v_exp_f32_e32 v101, v101
	v_add_f32_e32 v254, v96, v98
	s_waitcnt lgkmcnt(8)
	v_mfma_f32_32x32x16_bf16 v[16:31], v[224:227], v[216:219], v[16:31]
	ds_read_b64_tr_b16 v[240:241], v179 offset:9216
	ds_read_b64_tr_b16 v[242:243], v179 offset:11264
	v_exp_f32_e32 v102, v102
	v_exp_f32_e32 v103, v103
	v_add_f32_e32 v255, v97, v99
	v_mfma_f32_32x32x16_bf16 v[16:31], v[228:231], v[220:223], v[16:31]
	ds_read_b64_tr_b16 v[244:245], v179 offset:13312
	ds_read_b64_tr_b16 v[246:247], v179 offset:15360
	v_exp_f32_e32 v104, v104
	v_exp_f32_e32 v105, v105
	v_add_f32_e32 v254, v254, v100
	s_waitcnt lgkmcnt(8)
	v_mfma_f32_32x32x16_bf16 v[16:31], v[232:235], v[64:67], v[16:31]
	ds_read_b64_tr_b16 v[64:65], v179 offset:1536
	ds_read_b64_tr_b16 v[66:67], v179 offset:3584
	v_exp_f32_e32 v106, v106
	v_exp_f32_e32 v107, v107
	v_add_f32_e32 v255, v255, v101
	v_mfma_f32_32x32x16_bf16 v[16:31], v[236:239], v[68:71], v[16:31]
	ds_read_b64_tr_b16 v[68:69], v179 offset:5632
	ds_read_b64_tr_b16 v[70:71], v179 offset:7680
	v_exp_f32_e32 v108, v108
	v_exp_f32_e32 v109, v109
	v_add_f32_e32 v254, v254, v102
	s_waitcnt lgkmcnt(8)
	v_mfma_f32_32x32x16_bf16 v[32:47], v[224:227], v[72:75], v[32:47]
	ds_read_b64_tr_b16 v[72:73], v179 offset:9728
	ds_read_b64_tr_b16 v[74:75], v179 offset:11776
	v_exp_f32_e32 v110, v110
	v_exp_f32_e32 v111, v111
	v_add_f32_e32 v255, v255, v103
	v_mfma_f32_32x32x16_bf16 v[32:47], v[228:231], v[76:79], v[32:47]
	ds_read_b64_tr_b16 v[76:77], v179 offset:13824
	ds_read_b64_tr_b16 v[78:79], v179 offset:15872
	v_add_f32_e32 v254, v254, v104
	v_add_f32_e32 v255, v255, v105
	v_add_f32_e32 v254, v254, v106
	s_waitcnt lgkmcnt(8)
	v_mfma_f32_32x32x16_bf16 v[32:47], v[232:235], v[240:243], v[32:47]
	v_add_f32_e32 v255, v255, v107
	v_add_f32_e32 v254, v254, v108
	v_add_f32_e32 v255, v255, v109
	v_mfma_f32_32x32x16_bf16 v[32:47], v[236:239], v[244:247], v[32:47]
	v_add_f32_e32 v254, v254, v110
	v_add_f32_e32 v255, v255, v111
	s_waitcnt vmcnt(0)
	s_waitcnt lgkmcnt(0)
	s_barrier
; #define SBAR() __builtin_amdgcn_sched_barrier(0)
; __device__ __forceinline__ void partialSM_fix(f32x16& p0) { for (int r = 0; r < 16; ++r) p0[r] = __builtin_amdgcn_exp2f(p0[r]); }
; #define SLOAD(i, k0) do { sr_[i].vs0 = St::ld8(&Vh[(long)((k0) + sr) * LDK + sc]); sr_[i].vs1 = St::ld8(&Vh[(long)((k0) + 32 + sr) * LDK + sc]); \
;     sr_[i].ks0 = St::ld8(&Kh[(long)((k0) + sr) * LDK + sc]); sr_[i].ks1 = St::ld8(&Kh[(long)((k0) + 32 + sr) * LDK + sc]); } while (0)
; #define SWAIT() do { if constexpr (SDEPTH == 2) asm volatile("s_waitcnt vmcnt(4)" ::: "memory"); else asm volatile("s_waitcnt vmcnt(0)" ::: "memory"); } while (0)
; template <typename TQ>
; __device__ __forceinline__ void attn_dense_body(const TQ* __restrict__ Qb, const bf16* __restrict__ Kh, const bf16* __restrict__ Vh,
;                                                 bf16* __restrict__ Ob, int seq, char* lds) {
;     ...
;     SBAR(); qkt(pB0, pB1, (bf16*)((char*)K_lds + cur * (int)SHM_K), qr, r32, hi);
;     finishSM(pA0, pA1, alA, l_reg, pa0, pa1, pa2, pa3); SBAR();
;     SWAIT(); SWRITE(next, SE);
;     if (j + 2 < NT) SLOAD(SO, (j + 2) * KVBLK); SBAR();
;     pv_d0(o, vb0 + prev * (int)SHM_V, pa0, pa1, pa2, pa3); partialSM_fix(pB0);
;     __syncthreads();
;     { const int t_ = prev; prev = cur; cur = next; next = t_; }
;     SBAR(); qkt(pA0, pA1, (bf16*)((char*)K_lds + cur * (int)SHM_K), qr, r32, hi);
;     finishSM(pB0, pB1, alB, l_reg, pa0, pa1, pa2, pa3); SBAR();
;     if (j + 2 < NT) { SWAIT(); SWRITE(next, SO); }
;     if (j + 3 < NT) SLOAD(SE, (j + 3) * KVBLK); SBAR();
;     pv_d0(o, vb0 + prev * (int)SHM_V, pa0, pa1, pa2, pa3); partialSM_fix(pA0);
	ds_read_b128 v[208:211], v144 offset:32768
	ds_read_b128 v[212:215], v144 offset:40960
	ds_read_b128 v[216:219], v145 offset:32768
	ds_read_b128 v[220:223], v145 offset:40960
	ds_read_b128 v[240:243], v146 offset:32768
	ds_read_b128 v[244:247], v146 offset:40960
	v_mfma_f32_32x32x16_bf16 v[48:63], v[224:227], v[64:67], v[48:63]
	v_add_f32_e32 v254, v254, v255
	s_add_i32 m0, s80, 0x0
	s_add_u32 s96, s90, 0x80
	s_addc_u32 s97, s91, 0
	global_load_lds_dwordx4 v249, s[90:91]
	v_mfma_f32_32x32x16_bf16 v[48:63], v[228:231], v[68:71], v[48:63]
	s_add_i32 m0, s81, 0x0
	s_add_u32 s90, s90, 0x4000
	global_load_lds_dwordx4 v249, s[96:97]
	s_addc_u32 s91, s91, 0
	v_mfma_f32_32x32x16_bf16 v[48:63], v[232:235], v[72:75], v[48:63]
	s_add_i32 m0, s82, 0x0
	s_add_u32 s98, s92, 0x4000
	global_load_lds_dwordx4 v174, s[92:93]
	s_addc_u32 s99, s93, 0
	v_mfma_f32_32x32x16_bf16 v[48:63], v[236:239], v[76:79], v[48:63]
	s_add_i32 m0, s83, 0x0
	s_nop 0
	global_load_lds_dwordx4 v175, s[92:93]
	s_mov_b64 s[92:93], s[98:99]
	s_waitcnt lgkmcnt(4)
	v_mfma_f32_32x32x16_bf16 v[224:239], v[208:211], v[140:143], 0
	v_exp_f32_e32 v80, v80
	v_exp_f32_e32 v81, v81
	v_cvt_pk_bf16_f32 v96, v96, v97
	v_mfma_f32_32x32x16_bf16 v[64:79], v[212:215], v[140:143], 0
	ds_read_b128 v[208:211], v147 offset:32768
	ds_read_b128 v[212:215], v147 offset:40960
	v_exp_f32_e32 v82, v82
	v_exp_f32_e32 v83, v83
	v_cvt_pk_bf16_f32 v97, v98, v99
	s_waitcnt lgkmcnt(4)
	v_mfma_f32_32x32x16_bf16 v[224:239], v[216:219], v[136:139], v[224:239]
	v_exp_f32_e32 v84, v84
	v_exp_f32_e32 v85, v85
	v_cvt_pk_bf16_f32 v98, v100, v101
	v_mfma_f32_32x32x16_bf16 v[64:79], v[220:223], v[136:139], v[64:79]
	ds_read_b128 v[216:219], v148 offset:32768
	ds_read_b128 v[220:223], v148 offset:40960
	v_exp_f32_e32 v86, v86
	v_exp_f32_e32 v87, v87
	v_cvt_pk_bf16_f32 v99, v102, v103
	v_add_f32_e32 v251, v80, v82
	s_waitcnt lgkmcnt(4)
	v_mfma_f32_32x32x16_bf16 v[224:239], v[240:243], v[132:135], v[224:239]
	v_exp_f32_e32 v88, v88
	v_exp_f32_e32 v89, v89
	v_add_f32_e32 v253, v81, v83
	v_mfma_f32_32x32x16_bf16 v[64:79], v[244:247], v[132:135], v[64:79]
	ds_read_b128 v[240:243], v149 offset:32768
	ds_read_b128 v[244:247], v149 offset:40960
	v_exp_f32_e32 v90, v90
	v_exp_f32_e32 v91, v91
	v_add_f32_e32 v251, v251, v84
	s_waitcnt lgkmcnt(4)
	v_mfma_f32_32x32x16_bf16 v[224:239], v[208:211], v[128:131], v[224:239]
	v_exp_f32_e32 v92, v92
	v_exp_f32_e32 v93, v93
	v_add_f32_e32 v253, v253, v85
	v_cvt_pk_bf16_f32 v100, v104, v105
	v_mfma_f32_32x32x16_bf16 v[64:79], v[212:215], v[128:131], v[64:79]
	ds_read_b128 v[208:211], v150 offset:32768
	ds_read_b128 v[212:215], v150 offset:40960
	v_exp_f32_e32 v94, v94
	v_exp_f32_e32 v95, v95
	v_add_f32_e32 v251, v251, v86
	v_cvt_pk_bf16_f32 v101, v106, v107
	s_waitcnt lgkmcnt(4)
	v_mfma_f32_32x32x16_bf16 v[224:239], v[216:219], v[124:127], v[224:239]
	v_add_f32_e32 v253, v253, v87
	v_cvt_pk_bf16_f32 v102, v108, v109
	v_cvt_pk_bf16_f32 v103, v110, v111
	v_add_f32_e32 v251, v251, v88
	v_mfma_f32_32x32x16_bf16 v[64:79], v[220:223], v[124:127], v[64:79]
	ds_read_b128 v[216:219], v151 offset:32768
	ds_read_b128 v[220:223], v151 offset:40960
	v_add_f32_e32 v253, v253, v89
	v_cvt_pk_bf16_f32 v104, v80, v81
	v_cvt_pk_bf16_f32 v105, v82, v83
	s_waitcnt lgkmcnt(4)
	v_mfma_f32_32x32x16_bf16 v[224:239], v[240:243], v[120:123], v[224:239]
	v_add_f32_e32 v251, v251, v90
	v_cvt_pk_bf16_f32 v106, v84, v85
	v_cvt_pk_bf16_f32 v107, v86, v87
	v_mfma_f32_32x32x16_bf16 v[64:79], v[244:247], v[120:123], v[64:79]
	ds_read_b64_tr_b16 v[240:241], v179 offset:16384
	ds_read_b64_tr_b16 v[242:243], v179 offset:18432
	ds_read_b64_tr_b16 v[244:245], v179 offset:20480
	ds_read_b64_tr_b16 v[246:247], v179 offset:22528
	v_add_f32_e32 v253, v253, v91
	v_add_f32_e32 v251, v251, v92
	v_cvt_pk_bf16_f32 v108, v88, v89
	v_cvt_pk_bf16_f32 v109, v90, v91
	s_waitcnt lgkmcnt(6)
	v_mfma_f32_32x32x16_bf16 v[224:239], v[208:211], v[116:119], v[224:239]
	v_add_f32_e32 v253, v253, v93
	v_add_f32_e32 v251, v251, v94
	v_mfma_f32_32x32x16_bf16 v[64:79], v[212:215], v[116:119], v[64:79]
	ds_read_b64_tr_b16 v[208:209], v179 offset:24576
	ds_read_b64_tr_b16 v[210:211], v179 offset:26624
	ds_read_b64_tr_b16 v[212:213], v179 offset:28672
	ds_read_b64_tr_b16 v[214:215], v179 offset:30720
	v_add_f32_e32 v253, v253, v95
	v_cvt_pk_bf16_f32 v110, v92, v93
	v_cvt_pk_bf16_f32 v111, v94, v95
	s_waitcnt lgkmcnt(8)
	v_mfma_f32_32x32x16_bf16 v[224:239], v[216:219], v[112:115], v[224:239]
	v_add_f32_e32 v251, v251, v253
	v_add_f32_e32 v254, v254, v251
	v_mfma_f32_32x32x16_bf16 v[64:79], v[220:223], v[112:115], v[64:79]
	ds_read_b64_tr_b16 v[216:217], v179 offset:16896
	ds_read_b64_tr_b16 v[218:219], v179 offset:18944
	ds_read_b64_tr_b16 v[220:221], v179 offset:20992
	ds_read_b64_tr_b16 v[222:223], v179 offset:23040
	v_add_f32_e32 v169, v169, v254
	s_waitcnt lgkmcnt(8)
	v_mfma_f32_32x32x16_bf16 v[0:15], v[96:99], v[240:243], v[0:15]
	ds_read_b64_tr_b16 v[80:81], v179 offset:25088
	ds_read_b64_tr_b16 v[82:83], v179 offset:27136
	v_mfma_f32_32x32x16_bf16 v[0:15], v[100:103], v[244:247], v[0:15]
	ds_read_b64_tr_b16 v[84:85], v179 offset:29184
	ds_read_b64_tr_b16 v[86:87], v179 offset:31232
	v_exp_f32_e32 v224, v224
	v_exp_f32_e32 v225, v225
	s_waitcnt lgkmcnt(8)
	v_mfma_f32_32x32x16_bf16 v[0:15], v[104:107], v[208:211], v[0:15]
	ds_read_b64_tr_b16 v[88:89], v179 offset:17408
	ds_read_b64_tr_b16 v[90:91], v179 offset:19456
	v_exp_f32_e32 v226, v226
	v_exp_f32_e32 v227, v227
	v_mfma_f32_32x32x16_bf16 v[0:15], v[108:111], v[212:215], v[0:15]
	ds_read_b64_tr_b16 v[92:93], v179 offset:21504
	ds_read_b64_tr_b16 v[94:95], v179 offset:23552
	v_exp_f32_e32 v228, v228
	v_exp_f32_e32 v229, v229
	v_add_f32_e32 v254, v224, v226
	s_waitcnt lgkmcnt(8)
; __device__ __forceinline__ void finishSM(f32x16& p0, f32x16& p1, float alpha, float& l_reg, bf16x8& pa0, bf16x8& pa1, bf16x8& pa2, bf16x8& pa3) {
;   for (int r = 0; r < 16; ++r) p1[r] = __builtin_amdgcn_exp2f(p1[r]);
;   float ps = 0; for (int r = 0; r < 16; ++r) ps += p0[r]; for (int r = 0; r < 16; ++r) ps += p1[r];
;   { auto rr = __builtin_amdgcn_permlane32_swap(__float_as_uint(ps), __float_as_uint(ps), false, false);
;     ps = __uint_as_float(rr[0]) + __uint_as_float(rr[1]); }
;   l_reg = l_reg * alpha + ps;
;     ...
;   PK4(p0, 0, pa0); PK4(p0, 8, pa1); PK4(p1, 0, pa2); PK4(p1, 8, pa3);
;     ...
; }
; __device__ __forceinline__ void qkt(f32x16& p0, f32x16& p1, const bf16* Ks, const bf16x8* qr, int r32, int hi) {
;   p0 = f32x16{}; p1 = f32x16{};
;   for (int d0 = 0; d0 < 8; ++d0) { int cb = (d0 * 16 + hi * 8) * 2;
;     bf16x8 b0 = *reinterpret_cast<const bf16x8*>((const char*)Ks + KSWZ(r32, cb));
;     bf16x8 b1 = *reinterpret_cast<const bf16x8*>((const char*)Ks + KSWZ(32 + r32, cb));
;     p0 = __builtin_amdgcn_mfma_f32_32x32x16_bf16(b0, qr[d0], p0, 0, 0, 0);
;     p1 = __builtin_amdgcn_mfma_f32_32x32x16_bf16(b1, qr[d0], p1, 0, 0, 0); }
; }
; __device__ __forceinline__ int v_st(int k, int c) { const int kk = (k & ~0xC) | ((k & 4) << 1) | ((k & 8) >> 1); return ((kk >> 3) * 4 + (c >> 5)) * 512 + ((kk & 7) * 32 + (c & 31)) * 2; }
; __device__ __forceinline__ int v_rd_base(int lane) { return ((lane & 3) << 3) | (((lane >> 2) & 3) << 6) | (((lane >> 4) & 1) << 5) | (((lane >> 5) & 1) << 8); }
; template <int OFF> __device__ __forceinline__ s16x4 tr_read(int vb) {
;   s16x4 r; asm volatile("ds_read_b64_tr_b16 %0, %1 offset:%2" : "=&v"(r) : "v"(vb), "i"(OFF) : "memory"); return r;
; }
; template <int D0> __device__ __forceinline__ void pv_one(f32x16& od, int vb, bf16x8 pa0, bf16x8 pa1, bf16x8 pa2, bf16x8 pa3) {
;   const s16x4 l0 = tr_read<v_rd_off(D0, 0, 0)>(vb), h0 = tr_read<v_rd_off(D0, 0, 1)>(vb), l1 = tr_read<v_rd_off(D0, 1, 0)>(vb), h1 = tr_read<v_rd_off(D0, 1, 1)>(vb);
;   const s16x4 l2 = tr_read<v_rd_off(D0, 2, 0)>(vb), h2 = tr_read<v_rd_off(D0, 2, 1)>(vb), l3 = tr_read<v_rd_off(D0, 3, 0)>(vb), h3 = tr_read<v_rd_off(D0, 3, 1)>(vb);
;   asm volatile("s_waitcnt lgkmcnt(0)" ::: "memory"); SBAR();
;     ...
;   od = __builtin_amdgcn_mfma_f32_32x32x16_bf16(pa0, PK(l0, h0), od, 0, 0, 0);
;   od = __builtin_amdgcn_mfma_f32_32x32x16_bf16(pa1, PK(l1, h1), od, 0, 0, 0);
	v_mfma_f32_32x32x16_bf16 v[16:31], v[96:99], v[216:219], v[16:31]
	ds_read_b64_tr_b16 v[240:241], v179 offset:25600
	ds_read_b64_tr_b16 v[242:243], v179 offset:27648
	v_exp_f32_e32 v230, v230
	v_exp_f32_e32 v231, v231
	v_add_f32_e32 v255, v225, v227
	v_mfma_f32_32x32x16_bf16 v[16:31], v[100:103], v[220:223], v[16:31]
	ds_read_b64_tr_b16 v[244:245], v179 offset:29696
	ds_read_b64_tr_b16 v[246:247], v179 offset:31744
	v_exp_f32_e32 v232, v232
	v_exp_f32_e32 v233, v233
	v_add_f32_e32 v254, v254, v228
	s_waitcnt lgkmcnt(8)
	v_mfma_f32_32x32x16_bf16 v[16:31], v[104:107], v[80:83], v[16:31]
	ds_read_b64_tr_b16 v[80:81], v179 offset:17920
	ds_read_b64_tr_b16 v[82:83], v179 offset:19968
	v_exp_f32_e32 v234, v234
	v_exp_f32_e32 v235, v235
	v_add_f32_e32 v255, v255, v229
	v_mfma_f32_32x32x16_bf16 v[16:31], v[108:111], v[84:87], v[16:31]
	ds_read_b64_tr_b16 v[84:85], v179 offset:22016
	ds_read_b64_tr_b16 v[86:87], v179 offset:24064
	v_exp_f32_e32 v236, v236
	v_exp_f32_e32 v237, v237
	v_add_f32_e32 v254, v254, v230
	s_waitcnt lgkmcnt(8)
	v_mfma_f32_32x32x16_bf16 v[32:47], v[96:99], v[88:91], v[32:47]
	ds_read_b64_tr_b16 v[88:89], v179 offset:26112
	ds_read_b64_tr_b16 v[90:91], v179 offset:28160
	v_exp_f32_e32 v238, v238
	v_exp_f32_e32 v239, v239
	v_add_f32_e32 v255, v255, v231
	v_mfma_f32_32x32x16_bf16 v[32:47], v[100:103], v[92:95], v[32:47]
	ds_read_b64_tr_b16 v[92:93], v179 offset:30208
	ds_read_b64_tr_b16 v[94:95], v179 offset:32256
	v_add_f32_e32 v254, v254, v232
	v_add_f32_e32 v255, v255, v233
	v_add_f32_e32 v254, v254, v234
	s_waitcnt lgkmcnt(8)
	v_mfma_f32_32x32x16_bf16 v[32:47], v[104:107], v[240:243], v[32:47]
	v_add_f32_e32 v255, v255, v235
	v_add_f32_e32 v254, v254, v236
	v_add_f32_e32 v255, v255, v237
	v_mfma_f32_32x32x16_bf16 v[32:47], v[108:111], v[244:247], v[32:47]
	v_add_f32_e32 v254, v254, v238
	v_add_f32_e32 v255, v255, v239
	s_waitcnt vmcnt(0)
	s_waitcnt lgkmcnt(0)
	s_barrier
	ds_read_b128 v[208:211], v144 offset:0
	ds_read_b128 v[212:215], v144 offset:8192
	ds_read_b128 v[216:219], v145 offset:0
	ds_read_b128 v[220:223], v145 offset:8192
	ds_read_b128 v[240:243], v146 offset:0
	ds_read_b128 v[244:247], v146 offset:8192
	v_mfma_f32_32x32x16_bf16 v[48:63], v[96:99], v[80:83], v[48:63]
	v_add_f32_e32 v254, v254, v255
	s_add_i32 m0, s80, 0x4000
	s_add_u32 s96, s90, 0x80
	s_addc_u32 s97, s91, 0
	global_load_lds_dwordx4 v249, s[90:91]
	v_mfma_f32_32x32x16_bf16 v[48:63], v[100:103], v[84:87], v[48:63]
	s_add_i32 m0, s81, 0x4000
	s_add_u32 s90, s90, 0x4000
	global_load_lds_dwordx4 v249, s[96:97]
	s_addc_u32 s91, s91, 0
	v_mfma_f32_32x32x16_bf16 v[48:63], v[104:107], v[88:91], v[48:63]
	s_add_i32 m0, s82, 0x4000
	s_add_u32 s98, s92, 0x4000
	global_load_lds_dwordx4 v174, s[92:93]
	s_addc_u32 s99, s93, 0
	v_mfma_f32_32x32x16_bf16 v[48:63], v[108:111], v[92:95], v[48:63]
	s_add_i32 m0, s83, 0x4000
	s_nop 0
	global_load_lds_dwordx4 v175, s[92:93]
	s_mov_b64 s[92:93], s[98:99]
	s_add_i32 s55, s55, 2
	s_cmp_ge_u32 s55, s32
	s_cbranch_scc1 .Latt_exit_0
	s_waitcnt lgkmcnt(4)
	v_mfma_f32_32x32x16_bf16 v[96:111], v[208:211], v[140:143], 0
	v_exp_f32_e32 v64, v64
	v_exp_f32_e32 v65, v65
	v_cvt_pk_bf16_f32 v224, v224, v225
	v_mfma_f32_32x32x16_bf16 v[80:95], v[212:215], v[140:143], 0
	ds_read_b128 v[208:211], v147 offset:0
	ds_read_b128 v[212:215], v147 offset:8192
	v_exp_f32_e32 v66, v66
	v_exp_f32_e32 v67, v67
	v_cvt_pk_bf16_f32 v225, v226, v227
	s_waitcnt lgkmcnt(4)
	v_mfma_f32_32x32x16_bf16 v[96:111], v[216:219], v[136:139], v[96:111]
	v_exp_f32_e32 v68, v68
	v_exp_f32_e32 v69, v69
	v_cvt_pk_bf16_f32 v226, v228, v229
	v_mfma_f32_32x32x16_bf16 v[80:95], v[220:223], v[136:139], v[80:95]
	ds_read_b128 v[216:219], v148 offset:0
	ds_read_b128 v[220:223], v148 offset:8192
	v_exp_f32_e32 v70, v70
	v_exp_f32_e32 v71, v71
	v_cvt_pk_bf16_f32 v227, v230, v231
	v_add_f32_e32 v251, v64, v66
	s_waitcnt lgkmcnt(4)
	v_mfma_f32_32x32x16_bf16 v[96:111], v[240:243], v[132:135], v[96:111]
	v_exp_f32_e32 v72, v72
	v_exp_f32_e32 v73, v73
	v_add_f32_e32 v253, v65, v67
	v_mfma_f32_32x32x16_bf16 v[80:95], v[244:247], v[132:135], v[80:95]
	ds_read_b128 v[240:243], v149 offset:0
	ds_read_b128 v[244:247], v149 offset:8192
	v_exp_f32_e32 v74, v74
	v_exp_f32_e32 v75, v75
	v_add_f32_e32 v251, v251, v68
	s_waitcnt lgkmcnt(4)
	v_mfma_f32_32x32x16_bf16 v[96:111], v[208:211], v[128:131], v[96:111]
	v_exp_f32_e32 v76, v76
	v_exp_f32_e32 v77, v77
	v_add_f32_e32 v253, v253, v69
	v_cvt_pk_bf16_f32 v228, v232, v233
	v_mfma_f32_32x32x16_bf16 v[80:95], v[212:215], v[128:131], v[80:95]
	ds_read_b128 v[208:211], v150 offset:0
	ds_read_b128 v[212:215], v150 offset:8192
	v_exp_f32_e32 v78, v78
	v_exp_f32_e32 v79, v79
	v_add_f32_e32 v251, v251, v70
	v_cvt_pk_bf16_f32 v229, v234, v235
	s_waitcnt lgkmcnt(4)
	v_mfma_f32_32x32x16_bf16 v[96:111], v[216:219], v[124:127], v[96:111]
	v_add_f32_e32 v253, v253, v71
	v_cvt_pk_bf16_f32 v230, v236, v237
	v_cvt_pk_bf16_f32 v231, v238, v239
	v_add_f32_e32 v251, v251, v72
	v_mfma_f32_32x32x16_bf16 v[80:95], v[220:223], v[124:127], v[80:95]
	ds_read_b128 v[216:219], v151 offset:0
	ds_read_b128 v[220:223], v151 offset:8192
	v_add_f32_e32 v253, v253, v73
	v_cvt_pk_bf16_f32 v232, v64, v65
	v_cvt_pk_bf16_f32 v233, v66, v67
	s_waitcnt lgkmcnt(4)
	v_mfma_f32_32x32x16_bf16 v[96:111], v[240:243], v[120:123], v[96:111]
	v_add_f32_e32 v251, v251, v74
	v_cvt_pk_bf16_f32 v234, v68, v69
	v_cvt_pk_bf16_f32 v235, v70, v71
	v_mfma_f32_32x32x16_bf16 v[80:95], v[244:247], v[120:123], v[80:95]
	ds_read_b64_tr_b16 v[240:241], v179 offset:32768
	ds_read_b64_tr_b16 v[242:243], v179 offset:34816
	ds_read_b64_tr_b16 v[244:245], v179 offset:36864
	ds_read_b64_tr_b16 v[246:247], v179 offset:38912
	v_add_f32_e32 v253, v253, v75
	v_add_f32_e32 v251, v251, v76
	v_cvt_pk_bf16_f32 v236, v72, v73
	v_cvt_pk_bf16_f32 v237, v74, v75
	s_waitcnt lgkmcnt(6)
; __device__ __forceinline__ void finishSM(f32x16& p0, f32x16& p1, float alpha, float& l_reg, bf16x8& pa0, bf16x8& pa1, bf16x8& pa2, bf16x8& pa3) {
;   for (int r = 0; r < 16; ++r) p1[r] = __builtin_amdgcn_exp2f(p1[r]);
;   float ps = 0; for (int r = 0; r < 16; ++r) ps += p0[r]; for (int r = 0; r < 16; ++r) ps += p1[r];
;   { auto rr = __builtin_amdgcn_permlane32_swap(__float_as_uint(ps), __float_as_uint(ps), false, false);
;     ps = __uint_as_float(rr[0]) + __uint_as_float(rr[1]); }
;   l_reg = l_reg * alpha + ps;
;     ...
;   PK4(p0, 0, pa0); PK4(p0, 8, pa1); PK4(p1, 0, pa2); PK4(p1, 8, pa3);
;     ...
; }
; __device__ __forceinline__ void qkt(f32x16& p0, f32x16& p1, const bf16* Ks, const bf16x8* qr, int r32, int hi) {
;   p0 = f32x16{}; p1 = f32x16{};
;   for (int d0 = 0; d0 < 8; ++d0) { int cb = (d0 * 16 + hi * 8) * 2;
;     bf16x8 b0 = *reinterpret_cast<const bf16x8*>((const char*)Ks + KSWZ(r32, cb));
;     bf16x8 b1 = *reinterpret_cast<const bf16x8*>((const char*)Ks + KSWZ(32 + r32, cb));
;     p0 = __builtin_amdgcn_mfma_f32_32x32x16_bf16(b0, qr[d0], p0, 0, 0, 0);
;     p1 = __builtin_amdgcn_mfma_f32_32x32x16_bf16(b1, qr[d0], p1, 0, 0, 0); }
; }
; __device__ __forceinline__ int v_st(int k, int c) { const int kk = (k & ~0xC) | ((k & 4) << 1) | ((k & 8) >> 1); return ((kk >> 3) * 4 + (c >> 5)) * 512 + ((kk & 7) * 32 + (c & 31)) * 2; }
; __device__ __forceinline__ int v_rd_base(int lane) { return ((lane & 3) << 3) | (((lane >> 2) & 3) << 6) | (((lane >> 4) & 1) << 5) | (((lane >> 5) & 1) << 8); }
; template <int OFF> __device__ __forceinline__ s16x4 tr_read(int vb) {
;   s16x4 r; asm volatile("ds_read_b64_tr_b16 %0, %1 offset:%2" : "=&v"(r) : "v"(vb), "i"(OFF) : "memory"); return r;
; }
; template <int D0> __device__ __forceinline__ void pv_one(f32x16& od, int vb, bf16x8 pa0, bf16x8 pa1, bf16x8 pa2, bf16x8 pa3) {
;   const s16x4 l0 = tr_read<v_rd_off(D0, 0, 0)>(vb), h0 = tr_read<v_rd_off(D0, 0, 1)>(vb), l1 = tr_read<v_rd_off(D0, 1, 0)>(vb), h1 = tr_read<v_rd_off(D0, 1, 1)>(vb);
;   const s16x4 l2 = tr_read<v_rd_off(D0, 2, 0)>(vb), h2 = tr_read<v_rd_off(D0, 2, 1)>(vb), l3 = tr_read<v_rd_off(D0, 3, 0)>(vb), h3 = tr_read<v_rd_off(D0, 3, 1)>(vb);
;   asm volatile("s_waitcnt lgkmcnt(0)" ::: "memory"); SBAR();
;     ...
;   od = __builtin_amdgcn_mfma_f32_32x32x16_bf16(pa0, PK(l0, h0), od, 0, 0, 0);
;   od = __builtin_amdgcn_mfma_f32_32x32x16_bf16(pa1, PK(l1, h1), od, 0, 0, 0);
	v_mfma_f32_32x32x16_bf16 v[96:111], v[208:211], v[116:119], v[96:111]
	v_add_f32_e32 v253, v253, v77
	v_add_f32_e32 v251, v251, v78
	v_mfma_f32_32x32x16_bf16 v[80:95], v[212:215], v[116:119], v[80:95]
	ds_read_b64_tr_b16 v[208:209], v179 offset:40960
	ds_read_b64_tr_b16 v[210:211], v179 offset:43008
	ds_read_b64_tr_b16 v[212:213], v179 offset:45056
	ds_read_b64_tr_b16 v[214:215], v179 offset:47104
	v_add_f32_e32 v253, v253, v79
	v_cvt_pk_bf16_f32 v238, v76, v77
	v_cvt_pk_bf16_f32 v239, v78, v79
	s_waitcnt lgkmcnt(8)
	v_mfma_f32_32x32x16_bf16 v[96:111], v[216:219], v[112:115], v[96:111]
	v_add_f32_e32 v251, v251, v253
	v_add_f32_e32 v254, v254, v251
	v_mfma_f32_32x32x16_bf16 v[80:95], v[220:223], v[112:115], v[80:95]
	ds_read_b64_tr_b16 v[216:217], v179 offset:33280
	ds_read_b64_tr_b16 v[218:219], v179 offset:35328
	ds_read_b64_tr_b16 v[220:221], v179 offset:37376
	ds_read_b64_tr_b16 v[222:223], v179 offset:39424
	v_add_f32_e32 v169, v169, v254
	s_waitcnt lgkmcnt(8)
	v_mfma_f32_32x32x16_bf16 v[0:15], v[224:227], v[240:243], v[0:15]
	ds_read_b64_tr_b16 v[64:65], v179 offset:41472
	ds_read_b64_tr_b16 v[66:67], v179 offset:43520
	v_mfma_f32_32x32x16_bf16 v[0:15], v[228:231], v[244:247], v[0:15]
	ds_read_b64_tr_b16 v[68:69], v179 offset:45568
	ds_read_b64_tr_b16 v[70:71], v179 offset:47616
	v_exp_f32_e32 v96, v96
	v_exp_f32_e32 v97, v97
	s_waitcnt lgkmcnt(8)
	v_mfma_f32_32x32x16_bf16 v[0:15], v[232:235], v[208:211], v[0:15]
	ds_read_b64_tr_b16 v[72:73], v179 offset:33792
	ds_read_b64_tr_b16 v[74:75], v179 offset:35840
	v_exp_f32_e32 v98, v98
	v_exp_f32_e32 v99, v99
	v_mfma_f32_32x32x16_bf16 v[0:15], v[236:239], v[212:215], v[0:15]
	ds_read_b64_tr_b16 v[76:77], v179 offset:37888
	ds_read_b64_tr_b16 v[78:79], v179 offset:39936
	v_exp_f32_e32 v100, v100
	v_exp_f32_e32 v101, v101
	v_add_f32_e32 v254, v96, v98
	s_waitcnt lgkmcnt(8)
	v_mfma_f32_32x32x16_bf16 v[16:31], v[224:227], v[216:219], v[16:31]
	ds_read_b64_tr_b16 v[240:241], v179 offset:41984
	ds_read_b64_tr_b16 v[242:243], v179 offset:44032
	v_exp_f32_e32 v102, v102
	v_exp_f32_e32 v103, v103
	v_add_f32_e32 v255, v97, v99
	v_mfma_f32_32x32x16_bf16 v[16:31], v[228:231], v[220:223], v[16:31]
	ds_read_b64_tr_b16 v[244:245], v179 offset:46080
	ds_read_b64_tr_b16 v[246:247], v179 offset:48128
	v_exp_f32_e32 v104, v104
	v_exp_f32_e32 v105, v105
	v_add_f32_e32 v254, v254, v100
	s_waitcnt lgkmcnt(8)
	v_mfma_f32_32x32x16_bf16 v[16:31], v[232:235], v[64:67], v[16:31]
	ds_read_b64_tr_b16 v[64:65], v179 offset:34304
	ds_read_b64_tr_b16 v[66:67], v179 offset:36352
	v_exp_f32_e32 v106, v106
	v_exp_f32_e32 v107, v107
	v_add_f32_e32 v255, v255, v101
	v_mfma_f32_32x32x16_bf16 v[16:31], v[236:239], v[68:71], v[16:31]
	ds_read_b64_tr_b16 v[68:69], v179 offset:38400
	ds_read_b64_tr_b16 v[70:71], v179 offset:40448
	v_exp_f32_e32 v108, v108
	v_exp_f32_e32 v109, v109
	v_add_f32_e32 v254, v254, v102
	s_waitcnt lgkmcnt(8)
	v_mfma_f32_32x32x16_bf16 v[32:47], v[224:227], v[72:75], v[32:47]
	ds_read_b64_tr_b16 v[72:73], v179 offset:42496
	ds_read_b64_tr_b16 v[74:75], v179 offset:44544
	v_exp_f32_e32 v110, v110
	v_exp_f32_e32 v111, v111
	v_add_f32_e32 v255, v255, v103
	v_mfma_f32_32x32x16_bf16 v[32:47], v[228:231], v[76:79], v[32:47]
	ds_read_b64_tr_b16 v[76:77], v179 offset:46592
	ds_read_b64_tr_b16 v[78:79], v179 offset:48640
	v_add_f32_e32 v254, v254, v104
	v_add_f32_e32 v255, v255, v105
	v_add_f32_e32 v254, v254, v106
	s_waitcnt lgkmcnt(8)
	v_mfma_f32_32x32x16_bf16 v[32:47], v[232:235], v[240:243], v[32:47]
	v_add_f32_e32 v255, v255, v107
	v_add_f32_e32 v254, v254, v108
	v_add_f32_e32 v255, v255, v109
	v_mfma_f32_32x32x16_bf16 v[32:47], v[236:239], v[244:247], v[32:47]
	v_add_f32_e32 v254, v254, v110
	v_add_f32_e32 v255, v255, v111
	s_waitcnt vmcnt(0)
	s_waitcnt lgkmcnt(0)
	s_barrier
	ds_read_b128 v[208:211], v144 offset:16384
	ds_read_b128 v[212:215], v144 offset:24576
	ds_read_b128 v[216:219], v145 offset:16384
	ds_read_b128 v[220:223], v145 offset:24576
	ds_read_b128 v[240:243], v146 offset:16384
	ds_read_b128 v[244:247], v146 offset:24576
	v_mfma_f32_32x32x16_bf16 v[48:63], v[224:227], v[64:67], v[48:63]
	v_add_f32_e32 v254, v254, v255
	s_add_i32 m0, s80, 0x8000
	s_add_u32 s96, s90, 0x80
	s_addc_u32 s97, s91, 0
	global_load_lds_dwordx4 v249, s[90:91]
	v_mfma_f32_32x32x16_bf16 v[48:63], v[228:231], v[68:71], v[48:63]
	s_add_i32 m0, s81, 0x8000
	s_add_u32 s90, s90, 0x4000
	global_load_lds_dwordx4 v249, s[96:97]
	s_addc_u32 s91, s91, 0
	v_mfma_f32_32x32x16_bf16 v[48:63], v[232:235], v[72:75], v[48:63]
	s_add_i32 m0, s82, 0x8000
	s_add_u32 s98, s92, 0x4000
	global_load_lds_dwordx4 v174, s[92:93]
	s_addc_u32 s99, s93, 0
	v_mfma_f32_32x32x16_bf16 v[48:63], v[236:239], v[76:79], v[48:63]
	s_add_i32 m0, s83, 0x8000
	s_nop 0
	global_load_lds_dwordx4 v175, s[92:93]
	s_mov_b64 s[92:93], s[98:99]
	s_waitcnt lgkmcnt(4)
	v_mfma_f32_32x32x16_bf16 v[224:239], v[208:211], v[140:143], 0
	v_exp_f32_e32 v80, v80
	v_exp_f32_e32 v81, v81
	v_cvt_pk_bf16_f32 v96, v96, v97
	v_mfma_f32_32x32x16_bf16 v[64:79], v[212:215], v[140:143], 0
	ds_read_b128 v[208:211], v147 offset:16384
	ds_read_b128 v[212:215], v147 offset:24576
	v_exp_f32_e32 v82, v82
	v_exp_f32_e32 v83, v83
	v_cvt_pk_bf16_f32 v97, v98, v99
	s_waitcnt lgkmcnt(4)
	v_mfma_f32_32x32x16_bf16 v[224:239], v[216:219], v[136:139], v[224:239]
	v_exp_f32_e32 v84, v84
	v_exp_f32_e32 v85, v85
	v_cvt_pk_bf16_f32 v98, v100, v101
	v_mfma_f32_32x32x16_bf16 v[64:79], v[220:223], v[136:139], v[64:79]
	ds_read_b128 v[216:219], v148 offset:16384
	ds_read_b128 v[220:223], v148 offset:24576
	v_exp_f32_e32 v86, v86
	v_exp_f32_e32 v87, v87
	v_cvt_pk_bf16_f32 v99, v102, v103
	v_add_f32_e32 v251, v80, v82
	s_waitcnt lgkmcnt(4)
; __device__ __forceinline__ void finishSM(f32x16& p0, f32x16& p1, float alpha, float& l_reg, bf16x8& pa0, bf16x8& pa1, bf16x8& pa2, bf16x8& pa3) {
;   for (int r = 0; r < 16; ++r) p1[r] = __builtin_amdgcn_exp2f(p1[r]);
;   float ps = 0; for (int r = 0; r < 16; ++r) ps += p0[r]; for (int r = 0; r < 16; ++r) ps += p1[r];
;   { auto rr = __builtin_amdgcn_permlane32_swap(__float_as_uint(ps), __float_as_uint(ps), false, false);
;     ps = __uint_as_float(rr[0]) + __uint_as_float(rr[1]); }
;   l_reg = l_reg * alpha + ps;
;     ...
;   PK4(p0, 0, pa0); PK4(p0, 8, pa1); PK4(p1, 0, pa2); PK4(p1, 8, pa3);
;     ...
; }
; __device__ __forceinline__ void qkt(f32x16& p0, f32x16& p1, const bf16* Ks, const bf16x8* qr, int r32, int hi) {
;   p0 = f32x16{}; p1 = f32x16{};
;   for (int d0 = 0; d0 < 8; ++d0) { int cb = (d0 * 16 + hi * 8) * 2;
;     bf16x8 b0 = *reinterpret_cast<const bf16x8*>((const char*)Ks + KSWZ(r32, cb));
;     bf16x8 b1 = *reinterpret_cast<const bf16x8*>((const char*)Ks + KSWZ(32 + r32, cb));
;     p0 = __builtin_amdgcn_mfma_f32_32x32x16_bf16(b0, qr[d0], p0, 0, 0, 0);
;     p1 = __builtin_amdgcn_mfma_f32_32x32x16_bf16(b1, qr[d0], p1, 0, 0, 0); }
; }
; __device__ __forceinline__ int v_st(int k, int c) { const int kk = (k & ~0xC) | ((k & 4) << 1) | ((k & 8) >> 1); return ((kk >> 3) * 4 + (c >> 5)) * 512 + ((kk & 7) * 32 + (c & 31)) * 2; }
; __device__ __forceinline__ int v_rd_base(int lane) { return ((lane & 3) << 3) | (((lane >> 2) & 3) << 6) | (((lane >> 4) & 1) << 5) | (((lane >> 5) & 1) << 8); }
; template <int OFF> __device__ __forceinline__ s16x4 tr_read(int vb) {
;   s16x4 r; asm volatile("ds_read_b64_tr_b16 %0, %1 offset:%2" : "=&v"(r) : "v"(vb), "i"(OFF) : "memory"); return r;
; }
; template <int D0> __device__ __forceinline__ void pv_one(f32x16& od, int vb, bf16x8 pa0, bf16x8 pa1, bf16x8 pa2, bf16x8 pa3) {
;   const s16x4 l0 = tr_read<v_rd_off(D0, 0, 0)>(vb), h0 = tr_read<v_rd_off(D0, 0, 1)>(vb), l1 = tr_read<v_rd_off(D0, 1, 0)>(vb), h1 = tr_read<v_rd_off(D0, 1, 1)>(vb);
;   const s16x4 l2 = tr_read<v_rd_off(D0, 2, 0)>(vb), h2 = tr_read<v_rd_off(D0, 2, 1)>(vb), l3 = tr_read<v_rd_off(D0, 3, 0)>(vb), h3 = tr_read<v_rd_off(D0, 3, 1)>(vb);
;   asm volatile("s_waitcnt lgkmcnt(0)" ::: "memory"); SBAR();
;     ...
;   od = __builtin_amdgcn_mfma_f32_32x32x16_bf16(pa0, PK(l0, h0), od, 0, 0, 0);
;   od = __builtin_amdgcn_mfma_f32_32x32x16_bf16(pa1, PK(l1, h1), od, 0, 0, 0);
	v_mfma_f32_32x32x16_bf16 v[224:239], v[240:243], v[132:135], v[224:239]
	v_exp_f32_e32 v88, v88
	v_exp_f32_e32 v89, v89
	v_add_f32_e32 v253, v81, v83
	v_mfma_f32_32x32x16_bf16 v[64:79], v[244:247], v[132:135], v[64:79]
	ds_read_b128 v[240:243], v149 offset:16384
	ds_read_b128 v[244:247], v149 offset:24576
	v_exp_f32_e32 v90, v90
	v_exp_f32_e32 v91, v91
	v_add_f32_e32 v251, v251, v84
	s_waitcnt lgkmcnt(4)
	v_mfma_f32_32x32x16_bf16 v[224:239], v[208:211], v[128:131], v[224:239]
	v_exp_f32_e32 v92, v92
	v_exp_f32_e32 v93, v93
	v_add_f32_e32 v253, v253, v85
	v_cvt_pk_bf16_f32 v100, v104, v105
	v_mfma_f32_32x32x16_bf16 v[64:79], v[212:215], v[128:131], v[64:79]
	ds_read_b128 v[208:211], v150 offset:16384
	ds_read_b128 v[212:215], v150 offset:24576
	v_exp_f32_e32 v94, v94
	v_exp_f32_e32 v95, v95
	v_add_f32_e32 v251, v251, v86
	v_cvt_pk_bf16_f32 v101, v106, v107
	s_waitcnt lgkmcnt(4)
	v_mfma_f32_32x32x16_bf16 v[224:239], v[216:219], v[124:127], v[224:239]
	v_add_f32_e32 v253, v253, v87
	v_cvt_pk_bf16_f32 v102, v108, v109
	v_cvt_pk_bf16_f32 v103, v110, v111
	v_add_f32_e32 v251, v251, v88
	v_mfma_f32_32x32x16_bf16 v[64:79], v[220:223], v[124:127], v[64:79]
	ds_read_b128 v[216:219], v151 offset:16384
	ds_read_b128 v[220:223], v151 offset:24576
	v_add_f32_e32 v253, v253, v89
	v_cvt_pk_bf16_f32 v104, v80, v81
	v_cvt_pk_bf16_f32 v105, v82, v83
	s_waitcnt lgkmcnt(4)
	v_mfma_f32_32x32x16_bf16 v[224:239], v[240:243], v[120:123], v[224:239]
	v_add_f32_e32 v251, v251, v90
	v_cvt_pk_bf16_f32 v106, v84, v85
	v_cvt_pk_bf16_f32 v107, v86, v87
	v_mfma_f32_32x32x16_bf16 v[64:79], v[244:247], v[120:123], v[64:79]
	ds_read_b64_tr_b16 v[240:241], v179 offset:0
	ds_read_b64_tr_b16 v[242:243], v179 offset:2048
	ds_read_b64_tr_b16 v[244:245], v179 offset:4096
	ds_read_b64_tr_b16 v[246:247], v179 offset:6144
	v_add_f32_e32 v253, v253, v91
	v_add_f32_e32 v251, v251, v92
	v_cvt_pk_bf16_f32 v108, v88, v89
	v_cvt_pk_bf16_f32 v109, v90, v91
	s_waitcnt lgkmcnt(6)
	v_mfma_f32_32x32x16_bf16 v[224:239], v[208:211], v[116:119], v[224:239]
	v_add_f32_e32 v253, v253, v93
	v_add_f32_e32 v251, v251, v94
	v_mfma_f32_32x32x16_bf16 v[64:79], v[212:215], v[116:119], v[64:79]
	ds_read_b64_tr_b16 v[208:209], v179 offset:8192
	ds_read_b64_tr_b16 v[210:211], v179 offset:10240
	ds_read_b64_tr_b16 v[212:213], v179 offset:12288
	ds_read_b64_tr_b16 v[214:215], v179 offset:14336
	v_add_f32_e32 v253, v253, v95
	v_cvt_pk_bf16_f32 v110, v92, v93
	v_cvt_pk_bf16_f32 v111, v94, v95
	s_waitcnt lgkmcnt(8)
	v_mfma_f32_32x32x16_bf16 v[224:239], v[216:219], v[112:115], v[224:239]
	v_add_f32_e32 v251, v251, v253
	v_add_f32_e32 v254, v254, v251
	v_mfma_f32_32x32x16_bf16 v[64:79], v[220:223], v[112:115], v[64:79]
	ds_read_b64_tr_b16 v[216:217], v179 offset:512
	ds_read_b64_tr_b16 v[218:219], v179 offset:2560
	ds_read_b64_tr_b16 v[220:221], v179 offset:4608
	ds_read_b64_tr_b16 v[222:223], v179 offset:6656
	v_add_f32_e32 v169, v169, v254
	s_waitcnt lgkmcnt(8)
	v_mfma_f32_32x32x16_bf16 v[0:15], v[96:99], v[240:243], v[0:15]
	ds_read_b64_tr_b16 v[80:81], v179 offset:8704
	ds_read_b64_tr_b16 v[82:83], v179 offset:10752
	v_mfma_f32_32x32x16_bf16 v[0:15], v[100:103], v[244:247], v[0:15]
	ds_read_b64_tr_b16 v[84:85], v179 offset:12800
	ds_read_b64_tr_b16 v[86:87], v179 offset:14848
	v_exp_f32_e32 v224, v224
	v_exp_f32_e32 v225, v225
	s_waitcnt lgkmcnt(8)
	v_mfma_f32_32x32x16_bf16 v[0:15], v[104:107], v[208:211], v[0:15]
	ds_read_b64_tr_b16 v[88:89], v179 offset:1024
	ds_read_b64_tr_b16 v[90:91], v179 offset:3072
	v_exp_f32_e32 v226, v226
	v_exp_f32_e32 v227, v227
	v_mfma_f32_32x32x16_bf16 v[0:15], v[108:111], v[212:215], v[0:15]
	ds_read_b64_tr_b16 v[92:93], v179 offset:5120
	ds_read_b64_tr_b16 v[94:95], v179 offset:7168
	v_exp_f32_e32 v228, v228
	v_exp_f32_e32 v229, v229
	v_add_f32_e32 v254, v224, v226
	s_waitcnt lgkmcnt(8)
	v_mfma_f32_32x32x16_bf16 v[16:31], v[96:99], v[216:219], v[16:31]
	ds_read_b64_tr_b16 v[240:241], v179 offset:9216
	ds_read_b64_tr_b16 v[242:243], v179 offset:11264
	v_exp_f32_e32 v230, v230
	v_exp_f32_e32 v231, v231
	v_add_f32_e32 v255, v225, v227
	v_mfma_f32_32x32x16_bf16 v[16:31], v[100:103], v[220:223], v[16:31]
	ds_read_b64_tr_b16 v[244:245], v179 offset:13312
	ds_read_b64_tr_b16 v[246:247], v179 offset:15360
	v_exp_f32_e32 v232, v232
	v_exp_f32_e32 v233, v233
	v_add_f32_e32 v254, v254, v228
	s_waitcnt lgkmcnt(8)
	v_mfma_f32_32x32x16_bf16 v[16:31], v[104:107], v[80:83], v[16:31]
	ds_read_b64_tr_b16 v[80:81], v179 offset:1536
	ds_read_b64_tr_b16 v[82:83], v179 offset:3584
	v_exp_f32_e32 v234, v234
	v_exp_f32_e32 v235, v235
	v_add_f32_e32 v255, v255, v229
	v_mfma_f32_32x32x16_bf16 v[16:31], v[108:111], v[84:87], v[16:31]
	ds_read_b64_tr_b16 v[84:85], v179 offset:5632
	ds_read_b64_tr_b16 v[86:87], v179 offset:7680
	v_exp_f32_e32 v236, v236
	v_exp_f32_e32 v237, v237
	v_add_f32_e32 v254, v254, v230
	s_waitcnt lgkmcnt(8)
	v_mfma_f32_32x32x16_bf16 v[32:47], v[96:99], v[88:91], v[32:47]
	ds_read_b64_tr_b16 v[88:89], v179 offset:9728
	ds_read_b64_tr_b16 v[90:91], v179 offset:11776
	v_exp_f32_e32 v238, v238
	v_exp_f32_e32 v239, v239
	v_add_f32_e32 v255, v255, v231
	v_mfma_f32_32x32x16_bf16 v[32:47], v[100:103], v[92:95], v[32:47]
	ds_read_b64_tr_b16 v[92:93], v179 offset:13824
	ds_read_b64_tr_b16 v[94:95], v179 offset:15872
	v_add_f32_e32 v254, v254, v232
	v_add_f32_e32 v255, v255, v233
	v_add_f32_e32 v254, v254, v234
	s_waitcnt lgkmcnt(8)
	v_mfma_f32_32x32x16_bf16 v[32:47], v[104:107], v[240:243], v[32:47]
	v_add_f32_e32 v255, v255, v235
	v_add_f32_e32 v254, v254, v236
	v_add_f32_e32 v255, v255, v237
	v_mfma_f32_32x32x16_bf16 v[32:47], v[108:111], v[244:247], v[32:47]
	v_add_f32_e32 v254, v254, v238
	v_add_f32_e32 v255, v255, v239
	s_waitcnt vmcnt(0)
	s_waitcnt lgkmcnt(0)
	s_barrier
; __device__ __forceinline__ void finishSM(f32x16& p0, f32x16& p1, float alpha, float& l_reg, bf16x8& pa0, bf16x8& pa1, bf16x8& pa2, bf16x8& pa3) {
;   for (int r = 0; r < 16; ++r) p1[r] = __builtin_amdgcn_exp2f(p1[r]);
;   float ps = 0; for (int r = 0; r < 16; ++r) ps += p0[r]; for (int r = 0; r < 16; ++r) ps += p1[r];
;   { auto rr = __builtin_amdgcn_permlane32_swap(__float_as_uint(ps), __float_as_uint(ps), false, false);
;     ps = __uint_as_float(rr[0]) + __uint_as_float(rr[1]); }
;   l_reg = l_reg * alpha + ps;
;     ...
;   PK4(p0, 0, pa0); PK4(p0, 8, pa1); PK4(p1, 0, pa2); PK4(p1, 8, pa3);
;     ...
; }
; __device__ __forceinline__ void qkt(f32x16& p0, f32x16& p1, const bf16* Ks, const bf16x8* qr, int r32, int hi) {
;   p0 = f32x16{}; p1 = f32x16{};
;   for (int d0 = 0; d0 < 8; ++d0) { int cb = (d0 * 16 + hi * 8) * 2;
;     bf16x8 b0 = *reinterpret_cast<const bf16x8*>((const char*)Ks + KSWZ(r32, cb));
;     bf16x8 b1 = *reinterpret_cast<const bf16x8*>((const char*)Ks + KSWZ(32 + r32, cb));
;     p0 = __builtin_amdgcn_mfma_f32_32x32x16_bf16(b0, qr[d0], p0, 0, 0, 0);
;     p1 = __builtin_amdgcn_mfma_f32_32x32x16_bf16(b1, qr[d0], p1, 0, 0, 0); }
; }
; __device__ __forceinline__ int v_st(int k, int c) { const int kk = (k & ~0xC) | ((k & 4) << 1) | ((k & 8) >> 1); return ((kk >> 3) * 4 + (c >> 5)) * 512 + ((kk & 7) * 32 + (c & 31)) * 2; }
; __device__ __forceinline__ int v_rd_base(int lane) { return ((lane & 3) << 3) | (((lane >> 2) & 3) << 6) | (((lane >> 4) & 1) << 5) | (((lane >> 5) & 1) << 8); }
; template <int OFF> __device__ __forceinline__ s16x4 tr_read(int vb) {
;   s16x4 r; asm volatile("ds_read_b64_tr_b16 %0, %1 offset:%2" : "=&v"(r) : "v"(vb), "i"(OFF) : "memory"); return r;
; }
; template <int D0> __device__ __forceinline__ void pv_one(f32x16& od, int vb, bf16x8 pa0, bf16x8 pa1, bf16x8 pa2, bf16x8 pa3) {
;   const s16x4 l0 = tr_read<v_rd_off(D0, 0, 0)>(vb), h0 = tr_read<v_rd_off(D0, 0, 1)>(vb), l1 = tr_read<v_rd_off(D0, 1, 0)>(vb), h1 = tr_read<v_rd_off(D0, 1, 1)>(vb);
;   const s16x4 l2 = tr_read<v_rd_off(D0, 2, 0)>(vb), h2 = tr_read<v_rd_off(D0, 2, 1)>(vb), l3 = tr_read<v_rd_off(D0, 3, 0)>(vb), h3 = tr_read<v_rd_off(D0, 3, 1)>(vb);
;   asm volatile("s_waitcnt lgkmcnt(0)" ::: "memory"); SBAR();
;     ...
;   od = __builtin_amdgcn_mfma_f32_32x32x16_bf16(pa0, PK(l0, h0), od, 0, 0, 0);
;   od = __builtin_amdgcn_mfma_f32_32x32x16_bf16(pa1, PK(l1, h1), od, 0, 0, 0);
	ds_read_b128 v[208:211], v144 offset:32768
	ds_read_b128 v[212:215], v144 offset:40960
	ds_read_b128 v[216:219], v145 offset:32768
	ds_read_b128 v[220:223], v145 offset:40960
	ds_read_b128 v[240:243], v146 offset:32768
	ds_read_b128 v[244:247], v146 offset:40960
	v_mfma_f32_32x32x16_bf16 v[48:63], v[96:99], v[80:83], v[48:63]
	v_add_f32_e32 v254, v254, v255
	s_add_i32 m0, s80, 0x0
	s_add_u32 s96, s90, 0x80
	s_addc_u32 s97, s91, 0
	global_load_lds_dwordx4 v249, s[90:91]
	v_mfma_f32_32x32x16_bf16 v[48:63], v[100:103], v[84:87], v[48:63]
	s_add_i32 m0, s81, 0x0
	s_add_u32 s90, s90, 0x4000
	global_load_lds_dwordx4 v249, s[96:97]
	s_addc_u32 s91, s91, 0
	v_mfma_f32_32x32x16_bf16 v[48:63], v[104:107], v[88:91], v[48:63]
	s_add_i32 m0, s82, 0x0
	s_add_u32 s98, s92, 0x4000
	global_load_lds_dwordx4 v174, s[92:93]
	s_addc_u32 s99, s93, 0
	v_mfma_f32_32x32x16_bf16 v[48:63], v[108:111], v[92:95], v[48:63]
	s_add_i32 m0, s83, 0x0
	s_nop 0
	global_load_lds_dwordx4 v175, s[92:93]
	s_mov_b64 s[92:93], s[98:99]
	s_add_i32 s55, s55, 2
	s_cmp_ge_u32 s55, s32
	s_cbranch_scc1 .Latt_exit_1
	s_waitcnt lgkmcnt(4)
	v_mfma_f32_32x32x16_bf16 v[96:111], v[208:211], v[140:143], 0
	v_exp_f32_e32 v64, v64
	v_exp_f32_e32 v65, v65
	v_cvt_pk_bf16_f32 v224, v224, v225
	v_mfma_f32_32x32x16_bf16 v[80:95], v[212:215], v[140:143], 0
	ds_read_b128 v[208:211], v147 offset:32768
	ds_read_b128 v[212:215], v147 offset:40960
	v_exp_f32_e32 v66, v66
	v_exp_f32_e32 v67, v67
	v_cvt_pk_bf16_f32 v225, v226, v227
	s_waitcnt lgkmcnt(4)
	v_mfma_f32_32x32x16_bf16 v[96:111], v[216:219], v[136:139], v[96:111]
	v_exp_f32_e32 v68, v68
	v_exp_f32_e32 v69, v69
	v_cvt_pk_bf16_f32 v226, v228, v229
	v_mfma_f32_32x32x16_bf16 v[80:95], v[220:223], v[136:139], v[80:95]
	ds_read_b128 v[216:219], v148 offset:32768
	ds_read_b128 v[220:223], v148 offset:40960
	v_exp_f32_e32 v70, v70
	v_exp_f32_e32 v71, v71
	v_cvt_pk_bf16_f32 v227, v230, v231
	v_add_f32_e32 v251, v64, v66
	s_waitcnt lgkmcnt(4)
	v_mfma_f32_32x32x16_bf16 v[96:111], v[240:243], v[132:135], v[96:111]
	v_exp_f32_e32 v72, v72
	v_exp_f32_e32 v73, v73
	v_add_f32_e32 v253, v65, v67
	v_mfma_f32_32x32x16_bf16 v[80:95], v[244:247], v[132:135], v[80:95]
	ds_read_b128 v[240:243], v149 offset:32768
	ds_read_b128 v[244:247], v149 offset:40960
	v_exp_f32_e32 v74, v74
	v_exp_f32_e32 v75, v75
	v_add_f32_e32 v251, v251, v68
	s_waitcnt lgkmcnt(4)
	v_mfma_f32_32x32x16_bf16 v[96:111], v[208:211], v[128:131], v[96:111]
	v_exp_f32_e32 v76, v76
	v_exp_f32_e32 v77, v77
	v_add_f32_e32 v253, v253, v69
	v_cvt_pk_bf16_f32 v228, v232, v233
	v_mfma_f32_32x32x16_bf16 v[80:95], v[212:215], v[128:131], v[80:95]
	ds_read_b128 v[208:211], v150 offset:32768
	ds_read_b128 v[212:215], v150 offset:40960
	v_exp_f32_e32 v78, v78
	v_exp_f32_e32 v79, v79
	v_add_f32_e32 v251, v251, v70
	v_cvt_pk_bf16_f32 v229, v234, v235
	s_waitcnt lgkmcnt(4)
	v_mfma_f32_32x32x16_bf16 v[96:111], v[216:219], v[124:127], v[96:111]
	v_add_f32_e32 v253, v253, v71
	v_cvt_pk_bf16_f32 v230, v236, v237
	v_cvt_pk_bf16_f32 v231, v238, v239
	v_add_f32_e32 v251, v251, v72
	v_mfma_f32_32x32x16_bf16 v[80:95], v[220:223], v[124:127], v[80:95]
	ds_read_b128 v[216:219], v151 offset:32768
	ds_read_b128 v[220:223], v151 offset:40960
	v_add_f32_e32 v253, v253, v73
	v_cvt_pk_bf16_f32 v232, v64, v65
	v_cvt_pk_bf16_f32 v233, v66, v67
	s_waitcnt lgkmcnt(4)
	v_mfma_f32_32x32x16_bf16 v[96:111], v[240:243], v[120:123], v[96:111]
	v_add_f32_e32 v251, v251, v74
	v_cvt_pk_bf16_f32 v234, v68, v69
	v_cvt_pk_bf16_f32 v235, v70, v71
	v_mfma_f32_32x32x16_bf16 v[80:95], v[244:247], v[120:123], v[80:95]
	ds_read_b64_tr_b16 v[240:241], v179 offset:16384
	ds_read_b64_tr_b16 v[242:243], v179 offset:18432
	ds_read_b64_tr_b16 v[244:245], v179 offset:20480
	ds_read_b64_tr_b16 v[246:247], v179 offset:22528
	v_add_f32_e32 v253, v253, v75
	v_add_f32_e32 v251, v251, v76
	v_cvt_pk_bf16_f32 v236, v72, v73
	v_cvt_pk_bf16_f32 v237, v74, v75
	s_waitcnt lgkmcnt(6)
	v_mfma_f32_32x32x16_bf16 v[96:111], v[208:211], v[116:119], v[96:111]
	v_add_f32_e32 v253, v253, v77
	v_add_f32_e32 v251, v251, v78
	v_mfma_f32_32x32x16_bf16 v[80:95], v[212:215], v[116:119], v[80:95]
	ds_read_b64_tr_b16 v[208:209], v179 offset:24576
	ds_read_b64_tr_b16 v[210:211], v179 offset:26624
	ds_read_b64_tr_b16 v[212:213], v179 offset:28672
	ds_read_b64_tr_b16 v[214:215], v179 offset:30720
	v_add_f32_e32 v253, v253, v79
	v_cvt_pk_bf16_f32 v238, v76, v77
	v_cvt_pk_bf16_f32 v239, v78, v79
	s_waitcnt lgkmcnt(8)
	v_mfma_f32_32x32x16_bf16 v[96:111], v[216:219], v[112:115], v[96:111]
	v_add_f32_e32 v251, v251, v253
	v_add_f32_e32 v254, v254, v251
	v_mfma_f32_32x32x16_bf16 v[80:95], v[220:223], v[112:115], v[80:95]
	ds_read_b64_tr_b16 v[216:217], v179 offset:16896
	ds_read_b64_tr_b16 v[218:219], v179 offset:18944
	ds_read_b64_tr_b16 v[220:221], v179 offset:20992
	ds_read_b64_tr_b16 v[222:223], v179 offset:23040
	v_add_f32_e32 v169, v169, v254
	s_waitcnt lgkmcnt(8)
	v_mfma_f32_32x32x16_bf16 v[0:15], v[224:227], v[240:243], v[0:15]
	ds_read_b64_tr_b16 v[64:65], v179 offset:25088
	ds_read_b64_tr_b16 v[66:67], v179 offset:27136
	v_mfma_f32_32x32x16_bf16 v[0:15], v[228:231], v[244:247], v[0:15]
	ds_read_b64_tr_b16 v[68:69], v179 offset:29184
	ds_read_b64_tr_b16 v[70:71], v179 offset:31232
	v_exp_f32_e32 v96, v96
	v_exp_f32_e32 v97, v97
	s_waitcnt lgkmcnt(8)
	v_mfma_f32_32x32x16_bf16 v[0:15], v[232:235], v[208:211], v[0:15]
	ds_read_b64_tr_b16 v[72:73], v179 offset:17408
	ds_read_b64_tr_b16 v[74:75], v179 offset:19456
	v_exp_f32_e32 v98, v98
	v_exp_f32_e32 v99, v99
	v_mfma_f32_32x32x16_bf16 v[0:15], v[236:239], v[212:215], v[0:15]
	ds_read_b64_tr_b16 v[76:77], v179 offset:21504
	ds_read_b64_tr_b16 v[78:79], v179 offset:23552
	v_exp_f32_e32 v100, v100
	v_exp_f32_e32 v101, v101
	v_add_f32_e32 v254, v96, v98
	s_waitcnt lgkmcnt(8)
; __device__ __forceinline__ void finishSM(f32x16& p0, f32x16& p1, float alpha, float& l_reg, bf16x8& pa0, bf16x8& pa1, bf16x8& pa2, bf16x8& pa3) {
;   for (int r = 0; r < 16; ++r) p1[r] = __builtin_amdgcn_exp2f(p1[r]);
;   float ps = 0; for (int r = 0; r < 16; ++r) ps += p0[r]; for (int r = 0; r < 16; ++r) ps += p1[r];
;   { auto rr = __builtin_amdgcn_permlane32_swap(__float_as_uint(ps), __float_as_uint(ps), false, false);
;     ps = __uint_as_float(rr[0]) + __uint_as_float(rr[1]); }
;   l_reg = l_reg * alpha + ps;
;     ...
;   PK4(p0, 0, pa0); PK4(p0, 8, pa1); PK4(p1, 0, pa2); PK4(p1, 8, pa3);
;     ...
; }
; __device__ __forceinline__ void qkt(f32x16& p0, f32x16& p1, const bf16* Ks, const bf16x8* qr, int r32, int hi) {
;   p0 = f32x16{}; p1 = f32x16{};
;   for (int d0 = 0; d0 < 8; ++d0) { int cb = (d0 * 16 + hi * 8) * 2;
;     bf16x8 b0 = *reinterpret_cast<const bf16x8*>((const char*)Ks + KSWZ(r32, cb));
;     bf16x8 b1 = *reinterpret_cast<const bf16x8*>((const char*)Ks + KSWZ(32 + r32, cb));
;     p0 = __builtin_amdgcn_mfma_f32_32x32x16_bf16(b0, qr[d0], p0, 0, 0, 0);
;     p1 = __builtin_amdgcn_mfma_f32_32x32x16_bf16(b1, qr[d0], p1, 0, 0, 0); }
; }
; __device__ __forceinline__ int v_st(int k, int c) { const int kk = (k & ~0xC) | ((k & 4) << 1) | ((k & 8) >> 1); return ((kk >> 3) * 4 + (c >> 5)) * 512 + ((kk & 7) * 32 + (c & 31)) * 2; }
; __device__ __forceinline__ int v_rd_base(int lane) { return ((lane & 3) << 3) | (((lane >> 2) & 3) << 6) | (((lane >> 4) & 1) << 5) | (((lane >> 5) & 1) << 8); }
; template <int OFF> __device__ __forceinline__ s16x4 tr_read(int vb) {
;   s16x4 r; asm volatile("ds_read_b64_tr_b16 %0, %1 offset:%2" : "=&v"(r) : "v"(vb), "i"(OFF) : "memory"); return r;
; }
; template <int D0> __device__ __forceinline__ void pv_one(f32x16& od, int vb, bf16x8 pa0, bf16x8 pa1, bf16x8 pa2, bf16x8 pa3) {
;   const s16x4 l0 = tr_read<v_rd_off(D0, 0, 0)>(vb), h0 = tr_read<v_rd_off(D0, 0, 1)>(vb), l1 = tr_read<v_rd_off(D0, 1, 0)>(vb), h1 = tr_read<v_rd_off(D0, 1, 1)>(vb);
;   const s16x4 l2 = tr_read<v_rd_off(D0, 2, 0)>(vb), h2 = tr_read<v_rd_off(D0, 2, 1)>(vb), l3 = tr_read<v_rd_off(D0, 3, 0)>(vb), h3 = tr_read<v_rd_off(D0, 3, 1)>(vb);
;   asm volatile("s_waitcnt lgkmcnt(0)" ::: "memory"); SBAR();
;     ...
;   od = __builtin_amdgcn_mfma_f32_32x32x16_bf16(pa0, PK(l0, h0), od, 0, 0, 0);
;   od = __builtin_amdgcn_mfma_f32_32x32x16_bf16(pa1, PK(l1, h1), od, 0, 0, 0);
	v_mfma_f32_32x32x16_bf16 v[16:31], v[224:227], v[216:219], v[16:31]
	ds_read_b64_tr_b16 v[240:241], v179 offset:25600
	ds_read_b64_tr_b16 v[242:243], v179 offset:27648
	v_exp_f32_e32 v102, v102
	v_exp_f32_e32 v103, v103
	v_add_f32_e32 v255, v97, v99
	v_mfma_f32_32x32x16_bf16 v[16:31], v[228:231], v[220:223], v[16:31]
	ds_read_b64_tr_b16 v[244:245], v179 offset:29696
	ds_read_b64_tr_b16 v[246:247], v179 offset:31744
	v_exp_f32_e32 v104, v104
	v_exp_f32_e32 v105, v105
	v_add_f32_e32 v254, v254, v100
	s_waitcnt lgkmcnt(8)
	v_mfma_f32_32x32x16_bf16 v[16:31], v[232:235], v[64:67], v[16:31]
	ds_read_b64_tr_b16 v[64:65], v179 offset:17920
	ds_read_b64_tr_b16 v[66:67], v179 offset:19968
	v_exp_f32_e32 v106, v106
	v_exp_f32_e32 v107, v107
	v_add_f32_e32 v255, v255, v101
	v_mfma_f32_32x32x16_bf16 v[16:31], v[236:239], v[68:71], v[16:31]
	ds_read_b64_tr_b16 v[68:69], v179 offset:22016
	ds_read_b64_tr_b16 v[70:71], v179 offset:24064
	v_exp_f32_e32 v108, v108
	v_exp_f32_e32 v109, v109
	v_add_f32_e32 v254, v254, v102
	s_waitcnt lgkmcnt(8)
	v_mfma_f32_32x32x16_bf16 v[32:47], v[224:227], v[72:75], v[32:47]
	ds_read_b64_tr_b16 v[72:73], v179 offset:26112
	ds_read_b64_tr_b16 v[74:75], v179 offset:28160
	v_exp_f32_e32 v110, v110
	v_exp_f32_e32 v111, v111
	v_add_f32_e32 v255, v255, v103
	v_mfma_f32_32x32x16_bf16 v[32:47], v[228:231], v[76:79], v[32:47]
	ds_read_b64_tr_b16 v[76:77], v179 offset:30208
	ds_read_b64_tr_b16 v[78:79], v179 offset:32256
	v_add_f32_e32 v254, v254, v104
	v_add_f32_e32 v255, v255, v105
	v_add_f32_e32 v254, v254, v106
	s_waitcnt lgkmcnt(8)
	v_mfma_f32_32x32x16_bf16 v[32:47], v[232:235], v[240:243], v[32:47]
	v_add_f32_e32 v255, v255, v107
	v_add_f32_e32 v254, v254, v108
	v_add_f32_e32 v255, v255, v109
	v_mfma_f32_32x32x16_bf16 v[32:47], v[236:239], v[244:247], v[32:47]
	v_add_f32_e32 v254, v254, v110
	v_add_f32_e32 v255, v255, v111
	s_waitcnt vmcnt(0)
	s_waitcnt lgkmcnt(0)
	s_barrier
	ds_read_b128 v[208:211], v144 offset:0
	ds_read_b128 v[212:215], v144 offset:8192
	ds_read_b128 v[216:219], v145 offset:0
	ds_read_b128 v[220:223], v145 offset:8192
	ds_read_b128 v[240:243], v146 offset:0
	ds_read_b128 v[244:247], v146 offset:8192
	v_mfma_f32_32x32x16_bf16 v[48:63], v[224:227], v[64:67], v[48:63]
	v_add_f32_e32 v254, v254, v255
	s_add_i32 m0, s80, 0x4000
	s_add_u32 s96, s90, 0x80
	s_addc_u32 s97, s91, 0
	global_load_lds_dwordx4 v249, s[90:91]
	v_mfma_f32_32x32x16_bf16 v[48:63], v[228:231], v[68:71], v[48:63]
	s_add_i32 m0, s81, 0x4000
	s_add_u32 s90, s90, 0x4000
	global_load_lds_dwordx4 v249, s[96:97]
	s_addc_u32 s91, s91, 0
	v_mfma_f32_32x32x16_bf16 v[48:63], v[232:235], v[72:75], v[48:63]
	s_add_i32 m0, s82, 0x4000
	s_add_u32 s98, s92, 0x4000
	global_load_lds_dwordx4 v174, s[92:93]
	s_addc_u32 s99, s93, 0
	v_mfma_f32_32x32x16_bf16 v[48:63], v[236:239], v[76:79], v[48:63]
	s_add_i32 m0, s83, 0x4000
	s_nop 0
	global_load_lds_dwordx4 v175, s[92:93]
	s_mov_b64 s[92:93], s[98:99]
	s_waitcnt lgkmcnt(4)
	v_mfma_f32_32x32x16_bf16 v[224:239], v[208:211], v[140:143], 0
	v_exp_f32_e32 v80, v80
	v_exp_f32_e32 v81, v81
	v_cvt_pk_bf16_f32 v96, v96, v97
	v_mfma_f32_32x32x16_bf16 v[64:79], v[212:215], v[140:143], 0
	ds_read_b128 v[208:211], v147 offset:0
	ds_read_b128 v[212:215], v147 offset:8192
	v_exp_f32_e32 v82, v82
	v_exp_f32_e32 v83, v83
	v_cvt_pk_bf16_f32 v97, v98, v99
	s_waitcnt lgkmcnt(4)
	v_mfma_f32_32x32x16_bf16 v[224:239], v[216:219], v[136:139], v[224:239]
	v_exp_f32_e32 v84, v84
	v_exp_f32_e32 v85, v85
	v_cvt_pk_bf16_f32 v98, v100, v101
	v_mfma_f32_32x32x16_bf16 v[64:79], v[220:223], v[136:139], v[64:79]
	ds_read_b128 v[216:219], v148 offset:0
	ds_read_b128 v[220:223], v148 offset:8192
	v_exp_f32_e32 v86, v86
	v_exp_f32_e32 v87, v87
	v_cvt_pk_bf16_f32 v99, v102, v103
	v_add_f32_e32 v251, v80, v82
	s_waitcnt lgkmcnt(4)
	v_mfma_f32_32x32x16_bf16 v[224:239], v[240:243], v[132:135], v[224:239]
	v_exp_f32_e32 v88, v88
	v_exp_f32_e32 v89, v89
	v_add_f32_e32 v253, v81, v83
	v_mfma_f32_32x32x16_bf16 v[64:79], v[244:247], v[132:135], v[64:79]
	ds_read_b128 v[240:243], v149 offset:0
	ds_read_b128 v[244:247], v149 offset:8192
	v_exp_f32_e32 v90, v90
	v_exp_f32_e32 v91, v91
	v_add_f32_e32 v251, v251, v84
	s_waitcnt lgkmcnt(4)
	v_mfma_f32_32x32x16_bf16 v[224:239], v[208:211], v[128:131], v[224:239]
	v_exp_f32_e32 v92, v92
	v_exp_f32_e32 v93, v93
	v_add_f32_e32 v253, v253, v85
	v_cvt_pk_bf16_f32 v100, v104, v105
	v_mfma_f32_32x32x16_bf16 v[64:79], v[212:215], v[128:131], v[64:79]
	ds_read_b128 v[208:211], v150 offset:0
	ds_read_b128 v[212:215], v150 offset:8192
	v_exp_f32_e32 v94, v94
	v_exp_f32_e32 v95, v95
	v_add_f32_e32 v251, v251, v86
	v_cvt_pk_bf16_f32 v101, v106, v107
	s_waitcnt lgkmcnt(4)
	v_mfma_f32_32x32x16_bf16 v[224:239], v[216:219], v[124:127], v[224:239]
	v_add_f32_e32 v253, v253, v87
	v_cvt_pk_bf16_f32 v102, v108, v109
	v_cvt_pk_bf16_f32 v103, v110, v111
	v_add_f32_e32 v251, v251, v88
	v_mfma_f32_32x32x16_bf16 v[64:79], v[220:223], v[124:127], v[64:79]
	ds_read_b128 v[216:219], v151 offset:0
	ds_read_b128 v[220:223], v151 offset:8192
	v_add_f32_e32 v253, v253, v89
	v_cvt_pk_bf16_f32 v104, v80, v81
	v_cvt_pk_bf16_f32 v105, v82, v83
	s_waitcnt lgkmcnt(4)
; __device__ __forceinline__ void finishSM(f32x16& p0, f32x16& p1, float alpha, float& l_reg, bf16x8& pa0, bf16x8& pa1, bf16x8& pa2, bf16x8& pa3) {
;   for (int r = 0; r < 16; ++r) p1[r] = __builtin_amdgcn_exp2f(p1[r]);
;   float ps = 0; for (int r = 0; r < 16; ++r) ps += p0[r]; for (int r = 0; r < 16; ++r) ps += p1[r];
;   { auto rr = __builtin_amdgcn_permlane32_swap(__float_as_uint(ps), __float_as_uint(ps), false, false);
;     ps = __uint_as_float(rr[0]) + __uint_as_float(rr[1]); }
;   l_reg = l_reg * alpha + ps;
;     ...
;   PK4(p0, 0, pa0); PK4(p0, 8, pa1); PK4(p1, 0, pa2); PK4(p1, 8, pa3);
;     ...
; }
; __device__ __forceinline__ void qkt(f32x16& p0, f32x16& p1, const bf16* Ks, const bf16x8* qr, int r32, int hi) {
;   p0 = f32x16{}; p1 = f32x16{};
;   for (int d0 = 0; d0 < 8; ++d0) { int cb = (d0 * 16 + hi * 8) * 2;
;     bf16x8 b0 = *reinterpret_cast<const bf16x8*>((const char*)Ks + KSWZ(r32, cb));
;     bf16x8 b1 = *reinterpret_cast<const bf16x8*>((const char*)Ks + KSWZ(32 + r32, cb));
;     p0 = __builtin_amdgcn_mfma_f32_32x32x16_bf16(b0, qr[d0], p0, 0, 0, 0);
;     p1 = __builtin_amdgcn_mfma_f32_32x32x16_bf16(b1, qr[d0], p1, 0, 0, 0); }
; }
; __device__ __forceinline__ int v_st(int k, int c) { const int kk = (k & ~0xC) | ((k & 4) << 1) | ((k & 8) >> 1); return ((kk >> 3) * 4 + (c >> 5)) * 512 + ((kk & 7) * 32 + (c & 31)) * 2; }
; __device__ __forceinline__ int v_rd_base(int lane) { return ((lane & 3) << 3) | (((lane >> 2) & 3) << 6) | (((lane >> 4) & 1) << 5) | (((lane >> 5) & 1) << 8); }
; template <int OFF> __device__ __forceinline__ s16x4 tr_read(int vb) {
;   s16x4 r; asm volatile("ds_read_b64_tr_b16 %0, %1 offset:%2" : "=&v"(r) : "v"(vb), "i"(OFF) : "memory"); return r;
; }
; template <int D0> __device__ __forceinline__ void pv_one(f32x16& od, int vb, bf16x8 pa0, bf16x8 pa1, bf16x8 pa2, bf16x8 pa3) {
;   const s16x4 l0 = tr_read<v_rd_off(D0, 0, 0)>(vb), h0 = tr_read<v_rd_off(D0, 0, 1)>(vb), l1 = tr_read<v_rd_off(D0, 1, 0)>(vb), h1 = tr_read<v_rd_off(D0, 1, 1)>(vb);
;   const s16x4 l2 = tr_read<v_rd_off(D0, 2, 0)>(vb), h2 = tr_read<v_rd_off(D0, 2, 1)>(vb), l3 = tr_read<v_rd_off(D0, 3, 0)>(vb), h3 = tr_read<v_rd_off(D0, 3, 1)>(vb);
;   asm volatile("s_waitcnt lgkmcnt(0)" ::: "memory"); SBAR();
;     ...
;   od = __builtin_amdgcn_mfma_f32_32x32x16_bf16(pa0, PK(l0, h0), od, 0, 0, 0);
;   od = __builtin_amdgcn_mfma_f32_32x32x16_bf16(pa1, PK(l1, h1), od, 0, 0, 0);
	v_mfma_f32_32x32x16_bf16 v[224:239], v[240:243], v[120:123], v[224:239]
	v_add_f32_e32 v251, v251, v90
	v_cvt_pk_bf16_f32 v106, v84, v85
	v_cvt_pk_bf16_f32 v107, v86, v87
	v_mfma_f32_32x32x16_bf16 v[64:79], v[244:247], v[120:123], v[64:79]
	ds_read_b64_tr_b16 v[240:241], v179 offset:32768
	ds_read_b64_tr_b16 v[242:243], v179 offset:34816
	ds_read_b64_tr_b16 v[244:245], v179 offset:36864
	ds_read_b64_tr_b16 v[246:247], v179 offset:38912
	v_add_f32_e32 v253, v253, v91
	v_add_f32_e32 v251, v251, v92
	v_cvt_pk_bf16_f32 v108, v88, v89
	v_cvt_pk_bf16_f32 v109, v90, v91
	s_waitcnt lgkmcnt(6)
	v_mfma_f32_32x32x16_bf16 v[224:239], v[208:211], v[116:119], v[224:239]
	v_add_f32_e32 v253, v253, v93
	v_add_f32_e32 v251, v251, v94
	v_mfma_f32_32x32x16_bf16 v[64:79], v[212:215], v[116:119], v[64:79]
	ds_read_b64_tr_b16 v[208:209], v179 offset:40960
	ds_read_b64_tr_b16 v[210:211], v179 offset:43008
	ds_read_b64_tr_b16 v[212:213], v179 offset:45056
	ds_read_b64_tr_b16 v[214:215], v179 offset:47104
	v_add_f32_e32 v253, v253, v95
	v_cvt_pk_bf16_f32 v110, v92, v93
	v_cvt_pk_bf16_f32 v111, v94, v95
	s_waitcnt lgkmcnt(8)
	v_mfma_f32_32x32x16_bf16 v[224:239], v[216:219], v[112:115], v[224:239]
	v_add_f32_e32 v251, v251, v253
	v_add_f32_e32 v254, v254, v251
	v_mfma_f32_32x32x16_bf16 v[64:79], v[220:223], v[112:115], v[64:79]
	ds_read_b64_tr_b16 v[216:217], v179 offset:33280
	ds_read_b64_tr_b16 v[218:219], v179 offset:35328
	ds_read_b64_tr_b16 v[220:221], v179 offset:37376
	ds_read_b64_tr_b16 v[222:223], v179 offset:39424
	v_add_f32_e32 v169, v169, v254
	s_waitcnt lgkmcnt(8)
	v_mfma_f32_32x32x16_bf16 v[0:15], v[96:99], v[240:243], v[0:15]
	ds_read_b64_tr_b16 v[80:81], v179 offset:41472
	ds_read_b64_tr_b16 v[82:83], v179 offset:43520
	v_mfma_f32_32x32x16_bf16 v[0:15], v[100:103], v[244:247], v[0:15]
	ds_read_b64_tr_b16 v[84:85], v179 offset:45568
	ds_read_b64_tr_b16 v[86:87], v179 offset:47616
	v_exp_f32_e32 v224, v224
	v_exp_f32_e32 v225, v225
	s_waitcnt lgkmcnt(8)
	v_mfma_f32_32x32x16_bf16 v[0:15], v[104:107], v[208:211], v[0:15]
	ds_read_b64_tr_b16 v[88:89], v179 offset:33792
	ds_read_b64_tr_b16 v[90:91], v179 offset:35840
	v_exp_f32_e32 v226, v226
	v_exp_f32_e32 v227, v227
	v_mfma_f32_32x32x16_bf16 v[0:15], v[108:111], v[212:215], v[0:15]
	ds_read_b64_tr_b16 v[92:93], v179 offset:37888
	ds_read_b64_tr_b16 v[94:95], v179 offset:39936
	v_exp_f32_e32 v228, v228
	v_exp_f32_e32 v229, v229
	v_add_f32_e32 v254, v224, v226
	s_waitcnt lgkmcnt(8)
	v_mfma_f32_32x32x16_bf16 v[16:31], v[96:99], v[216:219], v[16:31]
	ds_read_b64_tr_b16 v[240:241], v179 offset:41984
	ds_read_b64_tr_b16 v[242:243], v179 offset:44032
	v_exp_f32_e32 v230, v230
	v_exp_f32_e32 v231, v231
	v_add_f32_e32 v255, v225, v227
	v_mfma_f32_32x32x16_bf16 v[16:31], v[100:103], v[220:223], v[16:31]
	ds_read_b64_tr_b16 v[244:245], v179 offset:46080
	ds_read_b64_tr_b16 v[246:247], v179 offset:48128
	v_exp_f32_e32 v232, v232
	v_exp_f32_e32 v233, v233
	v_add_f32_e32 v254, v254, v228
	s_waitcnt lgkmcnt(8)
	v_mfma_f32_32x32x16_bf16 v[16:31], v[104:107], v[80:83], v[16:31]
	ds_read_b64_tr_b16 v[80:81], v179 offset:34304
	ds_read_b64_tr_b16 v[82:83], v179 offset:36352
	v_exp_f32_e32 v234, v234
	v_exp_f32_e32 v235, v235
	v_add_f32_e32 v255, v255, v229
	v_mfma_f32_32x32x16_bf16 v[16:31], v[108:111], v[84:87], v[16:31]
	ds_read_b64_tr_b16 v[84:85], v179 offset:38400
	ds_read_b64_tr_b16 v[86:87], v179 offset:40448
	v_exp_f32_e32 v236, v236
	v_exp_f32_e32 v237, v237
	v_add_f32_e32 v254, v254, v230
	s_waitcnt lgkmcnt(8)
	v_mfma_f32_32x32x16_bf16 v[32:47], v[96:99], v[88:91], v[32:47]
	ds_read_b64_tr_b16 v[88:89], v179 offset:42496
	ds_read_b64_tr_b16 v[90:91], v179 offset:44544
	v_exp_f32_e32 v238, v238
	v_exp_f32_e32 v239, v239
	v_add_f32_e32 v255, v255, v231
	v_mfma_f32_32x32x16_bf16 v[32:47], v[100:103], v[92:95], v[32:47]
	ds_read_b64_tr_b16 v[92:93], v179 offset:46592
	ds_read_b64_tr_b16 v[94:95], v179 offset:48640
	v_add_f32_e32 v254, v254, v232
	v_add_f32_e32 v255, v255, v233
	v_add_f32_e32 v254, v254, v234
	s_waitcnt lgkmcnt(8)
	v_mfma_f32_32x32x16_bf16 v[32:47], v[104:107], v[240:243], v[32:47]
	v_add_f32_e32 v255, v255, v235
	v_add_f32_e32 v254, v254, v236
	v_add_f32_e32 v255, v255, v237
	v_mfma_f32_32x32x16_bf16 v[32:47], v[108:111], v[244:247], v[32:47]
	v_add_f32_e32 v254, v254, v238
	v_add_f32_e32 v255, v255, v239
	s_waitcnt vmcnt(0)
	s_waitcnt lgkmcnt(0)
	s_barrier
	ds_read_b128 v[208:211], v144 offset:16384
	ds_read_b128 v[212:215], v144 offset:24576
	ds_read_b128 v[216:219], v145 offset:16384
	ds_read_b128 v[220:223], v145 offset:24576
	ds_read_b128 v[240:243], v146 offset:16384
	ds_read_b128 v[244:247], v146 offset:24576
	v_mfma_f32_32x32x16_bf16 v[48:63], v[96:99], v[80:83], v[48:63]
	v_add_f32_e32 v254, v254, v255
	s_add_i32 m0, s80, 0x8000
	s_add_u32 s96, s90, 0x80
	s_addc_u32 s97, s91, 0
	global_load_lds_dwordx4 v249, s[90:91]
	v_mfma_f32_32x32x16_bf16 v[48:63], v[100:103], v[84:87], v[48:63]
	s_add_i32 m0, s81, 0x8000
	s_add_u32 s90, s90, 0x4000
	global_load_lds_dwordx4 v249, s[96:97]
	s_addc_u32 s91, s91, 0
	v_mfma_f32_32x32x16_bf16 v[48:63], v[104:107], v[88:91], v[48:63]
	s_add_i32 m0, s82, 0x8000
	s_add_u32 s98, s92, 0x4000
	global_load_lds_dwordx4 v174, s[92:93]
	s_addc_u32 s99, s93, 0
	v_mfma_f32_32x32x16_bf16 v[48:63], v[108:111], v[92:95], v[48:63]
	s_add_i32 m0, s83, 0x8000
	s_nop 0
	global_load_lds_dwordx4 v175, s[92:93]
	s_mov_b64 s[92:93], s[98:99]
	s_add_i32 s55, s55, 2
	s_cmp_ge_u32 s55, s32
	s_cbranch_scc1 .Latt_exit_2
	s_branch .Latt_loop
